# GEMM K-loops: removed compiler blanket vmcnt(0) before ds_read groups (template counted vmcnt(8) waits now effective); plus s6 epilogue load batching
# speedup vs baseline: 1.0385x; 1.0365x over previous
.LBB0_42:
	s_add_u32 s8, s4, s2
	s_addc_u32 s9, s5, 0
	s_add_u32 s3, s8, 0x100
	s_addc_u32 s10, s9, 0
	s_and_b64 s[6:7], s[84:85], exec
	s_cselect_b32 s7, s87, s10
	s_cselect_b32 s6, s86, s3
	s_add_u32 s2, s36, s2
	s_addc_u32 s3, s37, 0
	s_add_u32 s10, s2, 0x100
	ds_read_b128 v[128:131], v221
	ds_read_b128 v[132:135], v222
	ds_read_b128 v[136:139], v223
	ds_read_b128 v[140:143], v224
	ds_read_b128 v[144:147], v225
	ds_read_b128 v[148:151], v226
	ds_read_b128 v[152:155], v227
	ds_read_b128 v[156:159], v228
	s_addc_u32 s11, s3, 0
	s_and_b64 s[2:3], s[84:85], exec
	s_cselect_b32 vcc_hi, s89, s11
	s_cselect_b32 vcc_lo, s88, s10
	s_add_u32 s10, s8, 0x30080
	s_addc_u32 s11, s9, 0
	s_add_u32 s8, vcc_lo, 0x10000
	s_addc_u32 s9, vcc_hi, 0
	s_add_u32 s2, s6, 0x30000
	s_addc_u32 s3, s7, 0
	s_add_u32 s84, vcc_lo, 0x10080
	s_addc_u32 s85, vcc_hi, 0
	s_mov_b32 m0, s19
	v_lshl_add_u64 v[246:247], s[10:11], 0, v[192:193]
	ds_read_b128 v[160:163], v219
	ds_read_b128 v[164:167], v219 offset:1024
	ds_read_b128 v[168:171], v219 offset:2048
	ds_read_b128 v[172:175], v219 offset:3072
	ds_read_b128 v[198:201], v219 offset:4096
	ds_read_b128 v[202:205], v219 offset:5120
	ds_read_b128 v[238:241], v219 offset:6144
	ds_read_b128 v[242:245], v219 offset:7168
	global_load_lds_dwordx4 v[246:247], off
	v_lshl_add_u64 v[246:247], s[10:11], 0, v[188:189]
	s_mov_b32 m0, s74
	s_nop 0
	global_load_lds_dwordx4 v[246:247], off
	s_waitcnt vmcnt(8)
	s_waitcnt lgkmcnt(0)
	s_barrier
	s_setprio 1
	s_waitcnt lgkmcnt(0)
	v_mfma_f32_16x16x32_bf16 v[104:107], v[128:131], v[160:163], v[104:107]
	v_mfma_f32_16x16x32_bf16 v[124:127], v[136:139], v[160:163], v[124:127]
	v_mfma_f32_16x16x32_bf16 v[96:99], v[128:131], v[168:171], v[96:99]
	v_mfma_f32_16x16x32_bf16 v[120:123], v[136:139], v[168:171], v[120:123]
	v_mfma_f32_16x16x32_bf16 v[88:91], v[128:131], v[198:201], v[88:91]
	v_mfma_f32_16x16x32_bf16 v[116:119], v[136:139], v[198:201], v[116:119]
	v_mfma_f32_16x16x32_bf16 v[80:83], v[128:131], v[238:241], v[80:83]
	v_mfma_f32_16x16x32_bf16 v[112:115], v[136:139], v[238:241], v[112:115]
	v_mfma_f32_16x16x32_bf16 v[104:107], v[132:135], v[164:167], v[104:107]
	v_mfma_f32_16x16x32_bf16 v[124:127], v[140:143], v[164:167], v[124:127]
	v_mfma_f32_16x16x32_bf16 v[96:99], v[132:135], v[172:175], v[96:99]
	v_mfma_f32_16x16x32_bf16 v[120:123], v[140:143], v[172:175], v[120:123]
	v_mfma_f32_16x16x32_bf16 v[88:91], v[132:135], v[202:205], v[88:91]
	v_mfma_f32_16x16x32_bf16 v[116:119], v[140:143], v[202:205], v[116:119]
	v_mfma_f32_16x16x32_bf16 v[80:83], v[132:135], v[242:245], v[80:83]
	v_mfma_f32_16x16x32_bf16 v[112:115], v[140:143], v[242:245], v[112:115]
	s_setprio 0
	s_setprio 1
	v_mfma_f32_16x16x32_bf16 v[72:75], v[144:147], v[160:163], v[72:75]
	v_mfma_f32_16x16x32_bf16 v[108:111], v[152:155], v[160:163], v[108:111]
	v_mfma_f32_16x16x32_bf16 v[64:67], v[144:147], v[168:171], v[64:67]
	v_mfma_f32_16x16x32_bf16 v[100:103], v[152:155], v[168:171], v[100:103]
	v_mfma_f32_16x16x32_bf16 v[56:59], v[144:147], v[198:201], v[56:59]
	v_mfma_f32_16x16x32_bf16 v[92:95], v[152:155], v[198:201], v[92:95]
	v_mfma_f32_16x16x32_bf16 v[48:51], v[144:147], v[238:241], v[48:51]
	v_mfma_f32_16x16x32_bf16 v[84:87], v[152:155], v[238:241], v[84:87]
	v_mfma_f32_16x16x32_bf16 v[72:75], v[148:151], v[164:167], v[72:75]
	v_mfma_f32_16x16x32_bf16 v[108:111], v[156:159], v[164:167], v[108:111]
	v_mfma_f32_16x16x32_bf16 v[64:67], v[148:151], v[172:175], v[64:67]
	v_mfma_f32_16x16x32_bf16 v[100:103], v[156:159], v[172:175], v[100:103]
	v_mfma_f32_16x16x32_bf16 v[56:59], v[148:151], v[202:205], v[56:59]
	v_mfma_f32_16x16x32_bf16 v[92:95], v[156:159], v[202:205], v[92:95]
	v_mfma_f32_16x16x32_bf16 v[48:51], v[148:151], v[242:245], v[48:51]
	v_mfma_f32_16x16x32_bf16 v[84:87], v[156:159], v[242:245], v[84:87]
	s_setprio 0
	s_barrier
	s_mov_b32 m0, s23
	v_lshl_add_u64 v[246:247], vcc, 0, v[190:191]
	ds_read_b128 v[160:163], v219 offset:16384
	ds_read_b128 v[164:167], v219 offset:17408
	ds_read_b128 v[168:171], v219 offset:18432
	ds_read_b128 v[172:175], v219 offset:19456
	ds_read_b128 v[198:201], v219 offset:20480
	ds_read_b128 v[202:205], v219 offset:21504
	ds_read_b128 v[238:241], v219 offset:22528
	ds_read_b128 v[242:245], v219 offset:23552
	global_load_lds_dwordx4 v[246:247], off
	v_lshl_add_u64 v[248:249], vcc, 0, v[186:187]
	s_mov_b32 m0, s91
	v_lshl_add_u64 v[250:251], s[8:9], 0, v[190:191]
	global_load_lds_dwordx4 v[248:249], off
	s_mov_b32 m0, s21
	v_lshl_add_u64 v[252:253], s[6:7], 0, v[188:189]
	global_load_lds_dwordx4 v[250:251], off
	v_lshl_add_u64 v[250:251], s[8:9], 0, v[186:187]
	s_mov_b32 m0, s27
	s_nop 0
	global_load_lds_dwordx4 v[250:251], off
	v_lshl_add_u64 v[250:251], s[6:7], 0, v[192:193]
	s_mov_b32 m0, s43
	s_nop 0
	global_load_lds_dwordx4 v[250:251], off
	s_mov_b32 m0, s26
	s_nop 0
	global_load_lds_dwordx4 v[252:253], off
	s_waitcnt vmcnt(8)
	s_waitcnt lgkmcnt(0)
	s_barrier
	s_setprio 1
	s_waitcnt lgkmcnt(0)
	v_mfma_f32_16x16x32_bf16 v[40:43], v[128:131], v[160:163], v[40:43]
	v_mfma_f32_16x16x32_bf16 v[76:79], v[136:139], v[160:163], v[76:79]
	v_mfma_f32_16x16x32_bf16 v[32:35], v[128:131], v[168:171], v[32:35]
	v_mfma_f32_16x16x32_bf16 v[68:71], v[136:139], v[168:171], v[68:71]
	v_mfma_f32_16x16x32_bf16 v[24:27], v[128:131], v[198:201], v[24:27]
	v_mfma_f32_16x16x32_bf16 v[60:63], v[136:139], v[198:201], v[60:63]
	v_mfma_f32_16x16x32_bf16 v[20:23], v[128:131], v[238:241], v[20:23]
	v_mfma_f32_16x16x32_bf16 v[52:55], v[136:139], v[238:241], v[52:55]
	v_mfma_f32_16x16x32_bf16 v[40:43], v[132:135], v[164:167], v[40:43]
	v_mfma_f32_16x16x32_bf16 v[76:79], v[140:143], v[164:167], v[76:79]
	v_mfma_f32_16x16x32_bf16 v[32:35], v[132:135], v[172:175], v[32:35]
	v_mfma_f32_16x16x32_bf16 v[68:71], v[140:143], v[172:175], v[68:71]
	v_mfma_f32_16x16x32_bf16 v[24:27], v[132:135], v[202:205], v[24:27]
	v_mfma_f32_16x16x32_bf16 v[60:63], v[140:143], v[202:205], v[60:63]
	v_mfma_f32_16x16x32_bf16 v[20:23], v[132:135], v[242:245], v[20:23]
	v_mfma_f32_16x16x32_bf16 v[52:55], v[140:143], v[242:245], v[52:55]
	s_setprio 0
	s_setprio 1
	v_mfma_f32_16x16x32_bf16 v[16:19], v[144:147], v[160:163], v[16:19]
	v_mfma_f32_16x16x32_bf16 v[44:47], v[152:155], v[160:163], v[44:47]
	v_mfma_f32_16x16x32_bf16 v[12:15], v[144:147], v[168:171], v[12:15]
	v_mfma_f32_16x16x32_bf16 v[36:39], v[152:155], v[168:171], v[36:39]
	v_mfma_f32_16x16x32_bf16 v[4:7], v[144:147], v[198:201], v[4:7]
	v_mfma_f32_16x16x32_bf16 v[28:31], v[152:155], v[198:201], v[28:31]
	v_mfma_f32_16x16x32_bf16 v[0:3], v[144:147], v[238:241], v[0:3]
	v_mfma_f32_16x16x32_bf16 v[8:11], v[152:155], v[238:241], v[8:11]
	v_mfma_f32_16x16x32_bf16 v[16:19], v[148:151], v[164:167], v[16:19]
	v_mfma_f32_16x16x32_bf16 v[44:47], v[156:159], v[164:167], v[44:47]
	v_mfma_f32_16x16x32_bf16 v[12:15], v[148:151], v[172:175], v[12:15]
	v_mfma_f32_16x16x32_bf16 v[36:39], v[156:159], v[172:175], v[36:39]
	v_mfma_f32_16x16x32_bf16 v[4:7], v[148:151], v[202:205], v[4:7]
	v_mfma_f32_16x16x32_bf16 v[28:31], v[156:159], v[202:205], v[28:31]
	v_mfma_f32_16x16x32_bf16 v[0:3], v[148:151], v[242:245], v[0:3]
	v_mfma_f32_16x16x32_bf16 v[8:11], v[156:159], v[242:245], v[8:11]
	s_setprio 0
	s_barrier
	ds_read_b128 v[128:131], v229
	ds_read_b128 v[132:135], v230
	ds_read_b128 v[136:139], v231
	ds_read_b128 v[140:143], v232
	ds_read_b128 v[144:147], v233
	ds_read_b128 v[148:151], v234
	ds_read_b128 v[152:155], v235
	ds_read_b128 v[156:159], v236
	s_mov_b32 m0, s29
	v_lshl_add_u64 v[214:215], s[2:3], 0, v[192:193]
	ds_read_b128 v[160:163], v219 offset:32768
	ds_read_b128 v[164:167], v219 offset:33792
	ds_read_b128 v[168:171], v219 offset:34816
	ds_read_b128 v[172:175], v219 offset:35840
	ds_read_b128 v[198:201], v219 offset:36864
	ds_read_b128 v[202:205], v219 offset:37888
	ds_read_b128 v[238:241], v219 offset:38912
	ds_read_b128 v[242:245], v219 offset:39936
	global_load_lds_dwordx4 v[214:215], off
	v_lshl_add_u64 v[214:215], s[2:3], 0, v[188:189]
	s_mov_b32 m0, s28
	s_nop 0
	global_load_lds_dwordx4 v[214:215], off
	s_waitcnt vmcnt(8)
	s_waitcnt lgkmcnt(0)
	s_barrier
	s_setprio 1
	s_waitcnt lgkmcnt(0)
	v_mfma_f32_16x16x32_bf16 v[104:107], v[128:131], v[160:163], v[104:107]
	v_mfma_f32_16x16x32_bf16 v[124:127], v[136:139], v[160:163], v[124:127]
	v_mfma_f32_16x16x32_bf16 v[96:99], v[128:131], v[168:171], v[96:99]
	v_mfma_f32_16x16x32_bf16 v[120:123], v[136:139], v[168:171], v[120:123]
	v_mfma_f32_16x16x32_bf16 v[88:91], v[128:131], v[198:201], v[88:91]
	v_mfma_f32_16x16x32_bf16 v[116:119], v[136:139], v[198:201], v[116:119]
	v_mfma_f32_16x16x32_bf16 v[80:83], v[128:131], v[238:241], v[80:83]
	v_mfma_f32_16x16x32_bf16 v[112:115], v[136:139], v[238:241], v[112:115]
	v_mfma_f32_16x16x32_bf16 v[104:107], v[132:135], v[164:167], v[104:107]
	v_mfma_f32_16x16x32_bf16 v[124:127], v[140:143], v[164:167], v[124:127]
	v_mfma_f32_16x16x32_bf16 v[96:99], v[132:135], v[172:175], v[96:99]
	v_mfma_f32_16x16x32_bf16 v[120:123], v[140:143], v[172:175], v[120:123]
	v_mfma_f32_16x16x32_bf16 v[88:91], v[132:135], v[202:205], v[88:91]
	v_mfma_f32_16x16x32_bf16 v[116:119], v[140:143], v[202:205], v[116:119]
	v_mfma_f32_16x16x32_bf16 v[80:83], v[132:135], v[242:245], v[80:83]
	v_mfma_f32_16x16x32_bf16 v[112:115], v[140:143], v[242:245], v[112:115]
	s_setprio 0
	s_setprio 1
	v_mfma_f32_16x16x32_bf16 v[72:75], v[144:147], v[160:163], v[72:75]
	v_mfma_f32_16x16x32_bf16 v[108:111], v[152:155], v[160:163], v[108:111]
	v_mfma_f32_16x16x32_bf16 v[64:67], v[144:147], v[168:171], v[64:67]
	v_mfma_f32_16x16x32_bf16 v[100:103], v[152:155], v[168:171], v[100:103]
	v_mfma_f32_16x16x32_bf16 v[56:59], v[144:147], v[198:201], v[56:59]
	v_mfma_f32_16x16x32_bf16 v[92:95], v[152:155], v[198:201], v[92:95]
	v_mfma_f32_16x16x32_bf16 v[48:51], v[144:147], v[238:241], v[48:51]
	v_mfma_f32_16x16x32_bf16 v[84:87], v[152:155], v[238:241], v[84:87]
	v_mfma_f32_16x16x32_bf16 v[72:75], v[148:151], v[164:167], v[72:75]
	v_mfma_f32_16x16x32_bf16 v[108:111], v[156:159], v[164:167], v[108:111]
	v_mfma_f32_16x16x32_bf16 v[64:67], v[148:151], v[172:175], v[64:67]
	v_mfma_f32_16x16x32_bf16 v[100:103], v[156:159], v[172:175], v[100:103]
	v_mfma_f32_16x16x32_bf16 v[56:59], v[148:151], v[202:205], v[56:59]
	v_mfma_f32_16x16x32_bf16 v[92:95], v[156:159], v[202:205], v[92:95]
	v_mfma_f32_16x16x32_bf16 v[48:51], v[148:151], v[242:245], v[48:51]
	v_mfma_f32_16x16x32_bf16 v[84:87], v[156:159], v[242:245], v[84:87]
	s_setprio 0
	s_barrier
	s_mov_b32 m0, s31
	v_lshl_add_u64 v[214:215], v[246:247], 0, s[0:1]
	ds_read_b128 v[160:163], v219 offset:49152
	ds_read_b128 v[164:167], v219 offset:50176
	ds_read_b128 v[168:171], v219 offset:51200
	ds_read_b128 v[172:175], v219 offset:52224
	ds_read_b128 v[198:201], v219 offset:53248
	ds_read_b128 v[202:205], v219 offset:54272
	ds_read_b128 v[238:241], v219 offset:55296
	ds_read_b128 v[242:245], v219 offset:56320
	global_load_lds_dwordx4 v[214:215], off
	v_lshl_add_u64 v[214:215], v[248:249], 0, s[0:1]
	s_mov_b32 m0, s30
	s_nop 0
	global_load_lds_dwordx4 v[214:215], off
	v_lshl_add_u64 v[214:215], s[84:85], 0, v[190:191]
	s_mov_b32 m0, s95
	s_nop 0
	global_load_lds_dwordx4 v[214:215], off
	v_lshl_add_u64 v[214:215], s[84:85], 0, v[186:187]
	s_mov_b32 m0, s94
	s_nop 0
	global_load_lds_dwordx4 v[214:215], off
	v_lshl_add_u64 v[214:215], v[250:251], 0, s[0:1]
	s_mov_b32 m0, s35
	s_nop 0
	global_load_lds_dwordx4 v[214:215], off
	v_lshl_add_u64 v[214:215], v[252:253], 0, s[0:1]
	s_mov_b32 m0, s34
	s_nop 0
	global_load_lds_dwordx4 v[214:215], off
	s_waitcnt vmcnt(8)
	s_waitcnt lgkmcnt(0)
	s_barrier
	s_setprio 1
	s_waitcnt lgkmcnt(0)
	v_mfma_f32_16x16x32_bf16 v[40:43], v[128:131], v[160:163], v[40:43]
	v_mfma_f32_16x16x32_bf16 v[76:79], v[136:139], v[160:163], v[76:79]
	v_mfma_f32_16x16x32_bf16 v[32:35], v[128:131], v[168:171], v[32:35]
	v_mfma_f32_16x16x32_bf16 v[68:71], v[136:139], v[168:171], v[68:71]
	v_mfma_f32_16x16x32_bf16 v[24:27], v[128:131], v[198:201], v[24:27]
	v_mfma_f32_16x16x32_bf16 v[60:63], v[136:139], v[198:201], v[60:63]
	v_mfma_f32_16x16x32_bf16 v[20:23], v[128:131], v[238:241], v[20:23]
	v_mfma_f32_16x16x32_bf16 v[52:55], v[136:139], v[238:241], v[52:55]
	v_mfma_f32_16x16x32_bf16 v[40:43], v[132:135], v[164:167], v[40:43]
	v_mfma_f32_16x16x32_bf16 v[76:79], v[140:143], v[164:167], v[76:79]
	v_mfma_f32_16x16x32_bf16 v[32:35], v[132:135], v[172:175], v[32:35]
	v_mfma_f32_16x16x32_bf16 v[68:71], v[140:143], v[172:175], v[68:71]
	v_mfma_f32_16x16x32_bf16 v[24:27], v[132:135], v[202:205], v[24:27]
	v_mfma_f32_16x16x32_bf16 v[60:63], v[140:143], v[202:205], v[60:63]
	v_mfma_f32_16x16x32_bf16 v[20:23], v[132:135], v[242:245], v[20:23]
	v_mfma_f32_16x16x32_bf16 v[52:55], v[140:143], v[242:245], v[52:55]
	s_setprio 0
	s_setprio 1
	v_mfma_f32_16x16x32_bf16 v[16:19], v[144:147], v[160:163], v[16:19]
	v_mfma_f32_16x16x32_bf16 v[44:47], v[152:155], v[160:163], v[44:47]
	v_mfma_f32_16x16x32_bf16 v[12:15], v[144:147], v[168:171], v[12:15]
	v_mfma_f32_16x16x32_bf16 v[36:39], v[152:155], v[168:171], v[36:39]
	v_mfma_f32_16x16x32_bf16 v[4:7], v[144:147], v[198:201], v[4:7]
	v_mfma_f32_16x16x32_bf16 v[28:31], v[152:155], v[198:201], v[28:31]
	v_mfma_f32_16x16x32_bf16 v[0:3], v[144:147], v[238:241], v[0:3]
	v_mfma_f32_16x16x32_bf16 v[8:11], v[152:155], v[238:241], v[8:11]
	v_mfma_f32_16x16x32_bf16 v[16:19], v[148:151], v[164:167], v[16:19]
	v_mfma_f32_16x16x32_bf16 v[44:47], v[156:159], v[164:167], v[44:47]
	v_mfma_f32_16x16x32_bf16 v[12:15], v[148:151], v[172:175], v[12:15]
	v_mfma_f32_16x16x32_bf16 v[36:39], v[156:159], v[172:175], v[36:39]
	v_mfma_f32_16x16x32_bf16 v[4:7], v[148:151], v[202:205], v[4:7]
	v_mfma_f32_16x16x32_bf16 v[28:31], v[156:159], v[202:205], v[28:31]
	v_mfma_f32_16x16x32_bf16 v[0:3], v[148:151], v[242:245], v[0:3]
	v_mfma_f32_16x16x32_bf16 v[8:11], v[156:159], v[242:245], v[8:11]
	s_setprio 0
	s_barrier
	s_movk_i32 s2, 0x100
	s_andn2_b64 vcc, exec, s[38:39]
	s_mov_b64 s[84:85], -1
	s_mov_b64 s[38:39], 0
	s_cbranch_vccz .LBB0_42
	s_and_b64 vcc, exec, s[40:41]
	s_cbranch_vccz .LBB0_45
	s_barrier

.LBB0_157:
	v_or_b32_e32 v138, 0x10000, v142
	v_add_u32_e32 v139, 0x10400, v142
	ds_read_b128 v[144:147], v138
	ds_read_b128 v[148:151], v139
	v_add_u32_e32 v138, 0x10800, v142
	v_add_u32_e32 v139, 0x10c00, v142
	ds_read_b128 v[152:155], v138
	ds_read_b128 v[156:159], v139
	v_or_b32_e32 v138, 0x14000, v142
	v_add_u32_e32 v139, 0x14400, v142
	ds_read_b128 v[160:163], v138
	ds_read_b128 v[164:167], v139
	v_add_u32_e32 v138, 0x14800, v142
	v_add_u32_e32 v139, 0x14c00, v142
	ds_read_b128 v[168:171], v138
	ds_read_b128 v[172:175], v139
	s_add_u32 s8, vcc_lo, 0xfffc0080
	s_addc_u32 s9, vcc_hi, -1
	s_cmp_eq_u32 s90, 12
	s_cselect_b32 s11, s5, s9
	s_cselect_b32 s10, s92, s8
	s_cselect_b32 s9, s85, s89
	s_cselect_b32 s8, s96, s88
	v_lshl_add_u64 v[138:139], vcc, 0, v[134:135]
	s_add_i32 m0, s23, 0xc000
	ds_read_b128 v[186:189], v141
	ds_read_b128 v[190:193], v141 offset:1024
	ds_read_b128 v[194:197], v141 offset:2048
	ds_read_b128 v[198:201], v141 offset:3072
	ds_read_b128 v[202:205], v141 offset:4096
	ds_read_b128 v[220:223], v141 offset:5120
	ds_read_b128 v[224:227], v141 offset:6144
	ds_read_b128 v[228:231], v141 offset:7168
	global_load_lds_dwordx4 v[138:139], off
	v_lshl_add_u64 v[138:139], vcc, 0, v[136:137]
	s_add_i32 m0, s23, 0xe000
	s_nop 0
	global_load_lds_dwordx4 v[138:139], off
	s_waitcnt vmcnt(8)
	s_waitcnt lgkmcnt(0)
	s_barrier
	s_setprio 1
	s_waitcnt lgkmcnt(0)
	v_mfma_f32_16x16x32_bf16 v[124:127], v[144:147], v[186:189], v[124:127]
	v_mfma_f32_16x16x32_bf16 v[120:123], v[152:155], v[186:189], v[120:123]
	v_mfma_f32_16x16x32_bf16 v[108:111], v[144:147], v[194:197], v[108:111]
	v_mfma_f32_16x16x32_bf16 v[104:107], v[152:155], v[194:197], v[104:107]
	v_mfma_f32_16x16x32_bf16 v[92:95], v[144:147], v[202:205], v[92:95]
	v_mfma_f32_16x16x32_bf16 v[88:91], v[152:155], v[202:205], v[88:91]
	v_mfma_f32_16x16x32_bf16 v[76:79], v[144:147], v[224:227], v[76:79]
	v_mfma_f32_16x16x32_bf16 v[72:75], v[152:155], v[224:227], v[72:75]
	v_mfma_f32_16x16x32_bf16 v[124:127], v[148:151], v[190:193], v[124:127]
	v_mfma_f32_16x16x32_bf16 v[120:123], v[156:159], v[190:193], v[120:123]
	v_mfma_f32_16x16x32_bf16 v[108:111], v[148:151], v[198:201], v[108:111]
	v_mfma_f32_16x16x32_bf16 v[104:107], v[156:159], v[198:201], v[104:107]
	v_mfma_f32_16x16x32_bf16 v[92:95], v[148:151], v[220:223], v[92:95]
	v_mfma_f32_16x16x32_bf16 v[88:91], v[156:159], v[220:223], v[88:91]
	v_mfma_f32_16x16x32_bf16 v[76:79], v[148:151], v[228:231], v[76:79]
	v_mfma_f32_16x16x32_bf16 v[72:75], v[156:159], v[228:231], v[72:75]
	s_setprio 0
	s_setprio 1
	v_mfma_f32_16x16x32_bf16 v[116:119], v[160:163], v[186:189], v[116:119]
	v_mfma_f32_16x16x32_bf16 v[112:115], v[168:171], v[186:189], v[112:115]
	v_mfma_f32_16x16x32_bf16 v[100:103], v[160:163], v[194:197], v[100:103]
	v_mfma_f32_16x16x32_bf16 v[96:99], v[168:171], v[194:197], v[96:99]
	v_mfma_f32_16x16x32_bf16 v[84:87], v[160:163], v[202:205], v[84:87]
	v_mfma_f32_16x16x32_bf16 v[80:83], v[168:171], v[202:205], v[80:83]
	v_mfma_f32_16x16x32_bf16 v[68:71], v[160:163], v[224:227], v[68:71]
	v_mfma_f32_16x16x32_bf16 v[64:67], v[168:171], v[224:227], v[64:67]
	v_mfma_f32_16x16x32_bf16 v[116:119], v[164:167], v[190:193], v[116:119]
	v_mfma_f32_16x16x32_bf16 v[112:115], v[172:175], v[190:193], v[112:115]
	v_mfma_f32_16x16x32_bf16 v[100:103], v[164:167], v[198:201], v[100:103]
	v_mfma_f32_16x16x32_bf16 v[96:99], v[172:175], v[198:201], v[96:99]
	v_mfma_f32_16x16x32_bf16 v[84:87], v[164:167], v[220:223], v[84:87]
	v_mfma_f32_16x16x32_bf16 v[80:83], v[172:175], v[220:223], v[80:83]
	v_mfma_f32_16x16x32_bf16 v[68:71], v[164:167], v[228:231], v[68:71]
	v_mfma_f32_16x16x32_bf16 v[64:67], v[172:175], v[228:231], v[64:67]
	s_setprio 0
	s_barrier
	s_mov_b32 m0, s25
	v_lshl_add_u64 v[138:139], s[8:9], 0, v[176:177]
	s_add_u32 s60, s8, 0x40000
	ds_read_b128 v[186:189], v141 offset:16384
	ds_read_b128 v[190:193], v141 offset:17408
	ds_read_b128 v[194:197], v141 offset:18432
	ds_read_b128 v[198:201], v141 offset:19456
	ds_read_b128 v[202:205], v141 offset:20480
	ds_read_b128 v[220:223], v141 offset:21504
	ds_read_b128 v[224:227], v141 offset:22528
	ds_read_b128 v[228:231], v141 offset:23552
	global_load_lds_dwordx4 v[138:139], off
	v_lshl_add_u64 v[232:233], s[8:9], 0, v[128:129]
	s_mov_b32 m0, s26
	s_addc_u32 s61, s9, 0
	global_load_lds_dwordx4 v[232:233], off
	v_lshl_add_u64 v[234:235], s[60:61], 0, v[176:177]
	s_mov_b32 m0, s27
	v_lshl_add_u64 v[236:237], s[10:11], 0, v[130:131]
	global_load_lds_dwordx4 v[234:235], off
	v_lshl_add_u64 v[234:235], s[60:61], 0, v[128:129]
	s_mov_b32 m0, s28
	s_nop 0
	global_load_lds_dwordx4 v[234:235], off
	v_lshl_add_u64 v[234:235], s[10:11], 0, v[132:133]
	s_mov_b32 m0, s23
	s_nop 0
	global_load_lds_dwordx4 v[234:235], off
	s_mov_b32 m0, s29
	s_nop 0
	global_load_lds_dwordx4 v[236:237], off
	s_waitcnt vmcnt(8)
	s_waitcnt lgkmcnt(0)
	s_barrier
	s_setprio 1
	s_waitcnt lgkmcnt(0)
	v_mfma_f32_16x16x32_bf16 v[60:63], v[144:147], v[186:189], v[60:63]
	v_mfma_f32_16x16x32_bf16 v[56:59], v[152:155], v[186:189], v[56:59]
	v_mfma_f32_16x16x32_bf16 v[44:47], v[144:147], v[194:197], v[44:47]
	v_mfma_f32_16x16x32_bf16 v[40:43], v[152:155], v[194:197], v[40:43]
	v_mfma_f32_16x16x32_bf16 v[28:31], v[144:147], v[202:205], v[28:31]
	v_mfma_f32_16x16x32_bf16 v[24:27], v[152:155], v[202:205], v[24:27]
	v_mfma_f32_16x16x32_bf16 v[12:15], v[144:147], v[224:227], v[12:15]
	v_mfma_f32_16x16x32_bf16 v[8:11], v[152:155], v[224:227], v[8:11]
	v_mfma_f32_16x16x32_bf16 v[60:63], v[148:151], v[190:193], v[60:63]
	v_mfma_f32_16x16x32_bf16 v[56:59], v[156:159], v[190:193], v[56:59]
	v_mfma_f32_16x16x32_bf16 v[44:47], v[148:151], v[198:201], v[44:47]
	v_mfma_f32_16x16x32_bf16 v[40:43], v[156:159], v[198:201], v[40:43]
	v_mfma_f32_16x16x32_bf16 v[28:31], v[148:151], v[220:223], v[28:31]
	v_mfma_f32_16x16x32_bf16 v[24:27], v[156:159], v[220:223], v[24:27]
	v_mfma_f32_16x16x32_bf16 v[12:15], v[148:151], v[228:231], v[12:15]
	v_mfma_f32_16x16x32_bf16 v[8:11], v[156:159], v[228:231], v[8:11]
	s_setprio 0
	s_setprio 1
	v_mfma_f32_16x16x32_bf16 v[52:55], v[160:163], v[186:189], v[52:55]
	v_mfma_f32_16x16x32_bf16 v[48:51], v[168:171], v[186:189], v[48:51]
	v_mfma_f32_16x16x32_bf16 v[36:39], v[160:163], v[194:197], v[36:39]
	v_mfma_f32_16x16x32_bf16 v[32:35], v[168:171], v[194:197], v[32:35]
	v_mfma_f32_16x16x32_bf16 v[20:23], v[160:163], v[202:205], v[20:23]
	v_mfma_f32_16x16x32_bf16 v[16:19], v[168:171], v[202:205], v[16:19]
	v_mfma_f32_16x16x32_bf16 v[4:7], v[160:163], v[224:227], v[4:7]
	v_mfma_f32_16x16x32_bf16 v[0:3], v[168:171], v[224:227], v[0:3]
	v_mfma_f32_16x16x32_bf16 v[52:55], v[164:167], v[190:193], v[52:55]
	v_mfma_f32_16x16x32_bf16 v[48:51], v[172:175], v[190:193], v[48:51]
	v_mfma_f32_16x16x32_bf16 v[36:39], v[164:167], v[198:201], v[36:39]
	v_mfma_f32_16x16x32_bf16 v[32:35], v[172:175], v[198:201], v[32:35]
	v_mfma_f32_16x16x32_bf16 v[20:23], v[164:167], v[220:223], v[20:23]
	v_mfma_f32_16x16x32_bf16 v[16:19], v[172:175], v[220:223], v[16:19]
	v_mfma_f32_16x16x32_bf16 v[4:7], v[164:167], v[228:231], v[4:7]
	v_mfma_f32_16x16x32_bf16 v[0:3], v[172:175], v[228:231], v[0:3]
	s_setprio 0
	s_barrier
	v_or_b32_e32 v144, 0x18000, v142
	v_add_u32_e32 v148, 0x18400, v142
	v_add_u32_e32 v152, 0x18800, v142
	v_add_u32_e32 v156, 0x18c00, v142
	v_or_b32_e32 v160, 0x1c000, v142
	v_add_u32_e32 v164, 0x1c400, v142
	v_add_u32_e32 v168, 0x1c800, v142
	v_add_u32_e32 v172, 0x1cc00, v142
	ds_read_b128 v[144:147], v144
	ds_read_b128 v[148:151], v148
	ds_read_b128 v[152:155], v152
	ds_read_b128 v[156:159], v156
	ds_read_b128 v[160:163], v160
	ds_read_b128 v[164:167], v164
	ds_read_b128 v[168:171], v168
	ds_read_b128 v[172:175], v172
	s_add_u32 s10, s10, 0x40000
	s_addc_u32 s11, s11, 0
	s_mov_b32 m0, s30
	v_lshl_add_u64 v[238:239], s[10:11], 0, v[132:133]
	ds_read_b128 v[186:189], v141 offset:32768
	ds_read_b128 v[190:193], v141 offset:33792
	ds_read_b128 v[194:197], v141 offset:34816
	ds_read_b128 v[198:201], v141 offset:35840
	ds_read_b128 v[202:205], v141 offset:36864
	ds_read_b128 v[220:223], v141 offset:37888
	ds_read_b128 v[224:227], v141 offset:38912
	ds_read_b128 v[228:231], v141 offset:39936
	global_load_lds_dwordx4 v[238:239], off
	v_lshl_add_u64 v[238:239], s[10:11], 0, v[130:131]
	s_mov_b32 m0, s31
	s_nop 0
	global_load_lds_dwordx4 v[238:239], off
	s_waitcnt vmcnt(8)
	s_waitcnt lgkmcnt(0)
	s_barrier
	s_setprio 1
	s_waitcnt lgkmcnt(0)
	v_mfma_f32_16x16x32_bf16 v[124:127], v[144:147], v[186:189], v[124:127]
	v_mfma_f32_16x16x32_bf16 v[120:123], v[152:155], v[186:189], v[120:123]
	v_mfma_f32_16x16x32_bf16 v[108:111], v[144:147], v[194:197], v[108:111]
	v_mfma_f32_16x16x32_bf16 v[104:107], v[152:155], v[194:197], v[104:107]
	v_mfma_f32_16x16x32_bf16 v[92:95], v[144:147], v[202:205], v[92:95]
	v_mfma_f32_16x16x32_bf16 v[88:91], v[152:155], v[202:205], v[88:91]
	v_mfma_f32_16x16x32_bf16 v[76:79], v[144:147], v[224:227], v[76:79]
	v_mfma_f32_16x16x32_bf16 v[72:75], v[152:155], v[224:227], v[72:75]
	v_mfma_f32_16x16x32_bf16 v[124:127], v[148:151], v[190:193], v[124:127]
	v_mfma_f32_16x16x32_bf16 v[120:123], v[156:159], v[190:193], v[120:123]
	v_mfma_f32_16x16x32_bf16 v[108:111], v[148:151], v[198:201], v[108:111]
	v_mfma_f32_16x16x32_bf16 v[104:107], v[156:159], v[198:201], v[104:107]
	v_mfma_f32_16x16x32_bf16 v[92:95], v[148:151], v[220:223], v[92:95]
	v_mfma_f32_16x16x32_bf16 v[88:91], v[156:159], v[220:223], v[88:91]
	v_mfma_f32_16x16x32_bf16 v[76:79], v[148:151], v[228:231], v[76:79]
	v_mfma_f32_16x16x32_bf16 v[72:75], v[156:159], v[228:231], v[72:75]
	s_setprio 0
	s_setprio 1
	v_mfma_f32_16x16x32_bf16 v[116:119], v[160:163], v[186:189], v[116:119]
	v_mfma_f32_16x16x32_bf16 v[112:115], v[168:171], v[186:189], v[112:115]
	v_mfma_f32_16x16x32_bf16 v[100:103], v[160:163], v[194:197], v[100:103]
	v_mfma_f32_16x16x32_bf16 v[96:99], v[168:171], v[194:197], v[96:99]
	v_mfma_f32_16x16x32_bf16 v[84:87], v[160:163], v[202:205], v[84:87]
	v_mfma_f32_16x16x32_bf16 v[80:83], v[168:171], v[202:205], v[80:83]
	v_mfma_f32_16x16x32_bf16 v[68:71], v[160:163], v[224:227], v[68:71]
	v_mfma_f32_16x16x32_bf16 v[64:67], v[168:171], v[224:227], v[64:67]
	v_mfma_f32_16x16x32_bf16 v[116:119], v[164:167], v[190:193], v[116:119]
	v_mfma_f32_16x16x32_bf16 v[112:115], v[172:175], v[190:193], v[112:115]
	v_mfma_f32_16x16x32_bf16 v[100:103], v[164:167], v[198:201], v[100:103]
	v_mfma_f32_16x16x32_bf16 v[96:99], v[172:175], v[198:201], v[96:99]
	v_mfma_f32_16x16x32_bf16 v[84:87], v[164:167], v[220:223], v[84:87]
	v_mfma_f32_16x16x32_bf16 v[80:83], v[172:175], v[220:223], v[80:83]
	v_mfma_f32_16x16x32_bf16 v[68:71], v[164:167], v[228:231], v[68:71]
	v_mfma_f32_16x16x32_bf16 v[64:67], v[172:175], v[228:231], v[64:67]
	s_setprio 0
	s_barrier
	s_mov_b32 m0, s34
	v_lshl_add_u64 v[138:139], v[138:139], 0, s[0:1]
	s_add_u32 s8, s8, 0x40080
	ds_read_b128 v[186:189], v141 offset:49152
	ds_read_b128 v[190:193], v141 offset:50176
	ds_read_b128 v[194:197], v141 offset:51200
	ds_read_b128 v[198:201], v141 offset:52224
	ds_read_b128 v[202:205], v141 offset:53248
	ds_read_b128 v[220:223], v141 offset:54272
	ds_read_b128 v[224:227], v141 offset:55296
	ds_read_b128 v[228:231], v141 offset:56320
	global_load_lds_dwordx4 v[138:139], off
	v_lshl_add_u64 v[138:139], v[232:233], 0, s[0:1]
	s_mov_b32 m0, s35
	s_addc_u32 s9, s9, 0
	global_load_lds_dwordx4 v[138:139], off
	v_lshl_add_u64 v[138:139], s[8:9], 0, v[176:177]
	s_mov_b32 m0, s74
	s_nop 0
	global_load_lds_dwordx4 v[138:139], off
	v_lshl_add_u64 v[138:139], s[8:9], 0, v[128:129]
	s_mov_b32 m0, s75
	s_nop 0
	global_load_lds_dwordx4 v[138:139], off
	v_lshl_add_u64 v[138:139], v[234:235], 0, s[0:1]
	s_mov_b32 m0, s42
	s_nop 0
	global_load_lds_dwordx4 v[138:139], off
	v_lshl_add_u64 v[138:139], v[236:237], 0, s[0:1]
	s_mov_b32 m0, s43
	s_nop 0
	global_load_lds_dwordx4 v[138:139], off
	s_waitcnt vmcnt(8)
	s_waitcnt lgkmcnt(0)
	s_barrier
	s_setprio 1
	s_waitcnt lgkmcnt(0)
	v_mfma_f32_16x16x32_bf16 v[60:63], v[144:147], v[186:189], v[60:63]
	v_mfma_f32_16x16x32_bf16 v[56:59], v[152:155], v[186:189], v[56:59]
	v_mfma_f32_16x16x32_bf16 v[44:47], v[144:147], v[194:197], v[44:47]
	v_mfma_f32_16x16x32_bf16 v[40:43], v[152:155], v[194:197], v[40:43]
	v_mfma_f32_16x16x32_bf16 v[28:31], v[144:147], v[202:205], v[28:31]
	v_mfma_f32_16x16x32_bf16 v[24:27], v[152:155], v[202:205], v[24:27]
	v_mfma_f32_16x16x32_bf16 v[12:15], v[144:147], v[224:227], v[12:15]
	v_mfma_f32_16x16x32_bf16 v[8:11], v[152:155], v[224:227], v[8:11]
	v_mfma_f32_16x16x32_bf16 v[60:63], v[148:151], v[190:193], v[60:63]
	v_mfma_f32_16x16x32_bf16 v[56:59], v[156:159], v[190:193], v[56:59]
	v_mfma_f32_16x16x32_bf16 v[44:47], v[148:151], v[198:201], v[44:47]
	v_mfma_f32_16x16x32_bf16 v[40:43], v[156:159], v[198:201], v[40:43]
	v_mfma_f32_16x16x32_bf16 v[28:31], v[148:151], v[220:223], v[28:31]
	v_mfma_f32_16x16x32_bf16 v[24:27], v[156:159], v[220:223], v[24:27]
	v_mfma_f32_16x16x32_bf16 v[12:15], v[148:151], v[228:231], v[12:15]
	v_mfma_f32_16x16x32_bf16 v[8:11], v[156:159], v[228:231], v[8:11]
	s_setprio 0
	s_setprio 1
	v_mfma_f32_16x16x32_bf16 v[52:55], v[160:163], v[186:189], v[52:55]
	v_mfma_f32_16x16x32_bf16 v[48:51], v[168:171], v[186:189], v[48:51]
	v_mfma_f32_16x16x32_bf16 v[36:39], v[160:163], v[194:197], v[36:39]
	v_mfma_f32_16x16x32_bf16 v[32:35], v[168:171], v[194:197], v[32:35]
	v_mfma_f32_16x16x32_bf16 v[20:23], v[160:163], v[202:205], v[20:23]
	v_mfma_f32_16x16x32_bf16 v[16:19], v[168:171], v[202:205], v[16:19]
	v_mfma_f32_16x16x32_bf16 v[4:7], v[160:163], v[224:227], v[4:7]
	v_mfma_f32_16x16x32_bf16 v[0:3], v[168:171], v[224:227], v[0:3]
	v_mfma_f32_16x16x32_bf16 v[52:55], v[164:167], v[190:193], v[52:55]
	v_mfma_f32_16x16x32_bf16 v[48:51], v[172:175], v[190:193], v[48:51]
	v_mfma_f32_16x16x32_bf16 v[36:39], v[164:167], v[198:201], v[36:39]
	v_mfma_f32_16x16x32_bf16 v[32:35], v[172:175], v[198:201], v[32:35]
	v_mfma_f32_16x16x32_bf16 v[20:23], v[164:167], v[220:223], v[20:23]
	v_mfma_f32_16x16x32_bf16 v[16:19], v[172:175], v[220:223], v[16:19]
	v_mfma_f32_16x16x32_bf16 v[4:7], v[164:167], v[228:231], v[4:7]
	v_mfma_f32_16x16x32_bf16 v[0:3], v[172:175], v[228:231], v[0:3]
	s_setprio 0
	s_barrier
	s_add_i32 s90, s90, 2
	s_add_u32 vcc_lo, vcc_lo, 0x100
	s_addc_u32 vcc_hi, vcc_hi, 0
	s_add_u32 s88, s88, 0x100
	s_addc_u32 s89, s89, 0
	s_cmp_gt_u32 s90, 13
	s_cbranch_scc0 .LBB0_157
	s_and_b64 vcc, exec, s[40:41]
	s_cbranch_vccz .LBB0_160
	s_barrier

.LBB0_326:
	v_or_b32_e32 v13, 0x10000, v12
	v_add_u32_e32 v18, 0x10400, v12
	ds_read_b128 v[14:17], v13
	ds_read_b128 v[18:21], v18
	v_add_u32_e32 v13, 0x10800, v12
	v_add_u32_e32 v26, 0x10c00, v12
	s_add_u32 s2, s40, s90
	ds_read_b128 v[22:25], v13
	ds_read_b128 v[26:29], v26
	v_or_b32_e32 v13, 0x14000, v12
	s_addc_u32 s3, s41, s91
	v_add_u32_e32 v30, 0x14400, v12
	ds_read_b128 v[160:163], v13
	ds_read_b128 v[164:167], v30
	v_add_u32_e32 v13, 0x14800, v12
	s_add_u32 s2, s2, 0x100
	v_add_u32_e32 v30, 0x14c00, v12
	ds_read_b128 v[168:171], v13
	ds_read_b128 v[172:175], v30
	s_addc_u32 s3, s3, 0
	s_add_u32 s60, s75, s90
	s_addc_u32 s61, s83, s91
	s_cmpk_eq_i32 s90, 0x700
	s_cselect_b32 s7, s85, s3
	s_cselect_b32 s6, s92, s2
	s_cselect_b32 s3, s5, s61
	s_cselect_b32 s2, s94, s60
	v_lshl_add_u64 v[30:31], v[6:7], 0, s[90:91]
	s_add_i32 m0, s22, 0xc000
	ds_read_b128 v[186:189], v11
	ds_read_b128 v[194:197], v11 offset:1024
	ds_read_b128 v[198:201], v11 offset:2048
	ds_read_b128 v[202:205], v11 offset:3072
	ds_read_b128 v[220:223], v11 offset:4096
	ds_read_b128 v[224:227], v11 offset:5120
	ds_read_b128 v[228:231], v11 offset:6144
	ds_read_b128 v[232:235], v11 offset:7168
	global_load_lds_dwordx4 v[30:31], off
	v_lshl_add_u64 v[30:31], v[8:9], 0, s[90:91]
	s_add_i32 m0, s22, 0xe000
	s_nop 0
	global_load_lds_dwordx4 v[30:31], off
	s_waitcnt vmcnt(8)
	s_waitcnt lgkmcnt(0)
	s_barrier
	s_setprio 1
	s_waitcnt lgkmcnt(0)
	v_mfma_f32_16x16x32_bf16 v[156:159], v[14:17], v[186:189], v[156:159]
	v_mfma_f32_16x16x32_bf16 v[152:155], v[22:25], v[186:189], v[152:155]
	v_mfma_f32_16x16x32_bf16 v[140:143], v[14:17], v[198:201], v[140:143]
	v_mfma_f32_16x16x32_bf16 v[136:139], v[22:25], v[198:201], v[136:139]
	v_mfma_f32_16x16x32_bf16 v[124:127], v[14:17], v[220:223], v[124:127]
	v_mfma_f32_16x16x32_bf16 v[120:123], v[22:25], v[220:223], v[120:123]
	v_mfma_f32_16x16x32_bf16 v[108:111], v[14:17], v[228:231], v[108:111]
	v_mfma_f32_16x16x32_bf16 v[104:107], v[22:25], v[228:231], v[104:107]
	v_mfma_f32_16x16x32_bf16 v[156:159], v[18:21], v[194:197], v[156:159]
	v_mfma_f32_16x16x32_bf16 v[152:155], v[26:29], v[194:197], v[152:155]
	v_mfma_f32_16x16x32_bf16 v[140:143], v[18:21], v[202:205], v[140:143]
	v_mfma_f32_16x16x32_bf16 v[136:139], v[26:29], v[202:205], v[136:139]
	v_mfma_f32_16x16x32_bf16 v[124:127], v[18:21], v[224:227], v[124:127]
	v_mfma_f32_16x16x32_bf16 v[120:123], v[26:29], v[224:227], v[120:123]
	v_mfma_f32_16x16x32_bf16 v[108:111], v[18:21], v[232:235], v[108:111]
	v_mfma_f32_16x16x32_bf16 v[104:107], v[26:29], v[232:235], v[104:107]
	s_setprio 0
	s_setprio 1
	v_mfma_f32_16x16x32_bf16 v[148:151], v[160:163], v[186:189], v[148:151]
	v_mfma_f32_16x16x32_bf16 v[144:147], v[168:171], v[186:189], v[144:147]
	v_mfma_f32_16x16x32_bf16 v[132:135], v[160:163], v[198:201], v[132:135]
	v_mfma_f32_16x16x32_bf16 v[128:131], v[168:171], v[198:201], v[128:131]
	v_mfma_f32_16x16x32_bf16 v[116:119], v[160:163], v[220:223], v[116:119]
	v_mfma_f32_16x16x32_bf16 v[112:115], v[168:171], v[220:223], v[112:115]
	v_mfma_f32_16x16x32_bf16 v[100:103], v[160:163], v[228:231], v[100:103]
	v_mfma_f32_16x16x32_bf16 v[96:99], v[168:171], v[228:231], v[96:99]
	v_mfma_f32_16x16x32_bf16 v[148:151], v[164:167], v[194:197], v[148:151]
	v_mfma_f32_16x16x32_bf16 v[144:147], v[172:175], v[194:197], v[144:147]
	v_mfma_f32_16x16x32_bf16 v[132:135], v[164:167], v[202:205], v[132:135]
	v_mfma_f32_16x16x32_bf16 v[128:131], v[172:175], v[202:205], v[128:131]
	v_mfma_f32_16x16x32_bf16 v[116:119], v[164:167], v[224:227], v[116:119]
	v_mfma_f32_16x16x32_bf16 v[112:115], v[172:175], v[224:227], v[112:115]
	v_mfma_f32_16x16x32_bf16 v[100:103], v[164:167], v[232:235], v[100:103]
	v_mfma_f32_16x16x32_bf16 v[96:99], v[172:175], v[232:235], v[96:99]
	s_setprio 0
	s_barrier
	s_mov_b32 m0, s23
	v_lshl_add_u64 v[190:191], s[2:3], 0, v[176:177]
	s_add_u32 s60, s2, 0x40000
	ds_read_b128 v[186:189], v11 offset:16384
	ds_read_b128 v[194:197], v11 offset:17408
	ds_read_b128 v[198:201], v11 offset:18432
	ds_read_b128 v[202:205], v11 offset:19456
	ds_read_b128 v[220:223], v11 offset:20480
	ds_read_b128 v[224:227], v11 offset:21504
	ds_read_b128 v[228:231], v11 offset:22528
	ds_read_b128 v[232:235], v11 offset:23552
	global_load_lds_dwordx4 v[190:191], off
	v_lshl_add_u64 v[214:215], s[2:3], 0, v[0:1]
	s_mov_b32 m0, s24
	s_addc_u32 s61, s3, 0
	global_load_lds_dwordx4 v[214:215], off
	v_lshl_add_u64 v[30:31], s[60:61], 0, v[176:177]
	s_mov_b32 m0, s25
	v_lshl_add_u64 v[236:237], s[6:7], 0, v[176:177]
	global_load_lds_dwordx4 v[30:31], off
	v_lshl_add_u64 v[30:31], s[60:61], 0, v[0:1]
	s_mov_b32 m0, s26
	v_lshl_add_u64 v[238:239], s[6:7], 0, v[0:1]
	global_load_lds_dwordx4 v[30:31], off
	s_mov_b32 m0, s22
	s_nop 0
	global_load_lds_dwordx4 v[236:237], off
	s_mov_b32 m0, s27
	s_nop 0
	global_load_lds_dwordx4 v[238:239], off
	s_waitcnt vmcnt(8)
	s_waitcnt lgkmcnt(0)
	s_barrier
	s_setprio 1
	s_waitcnt lgkmcnt(0)
	v_mfma_f32_16x16x32_bf16 v[92:95], v[14:17], v[186:189], v[92:95]
	v_mfma_f32_16x16x32_bf16 v[88:91], v[22:25], v[186:189], v[88:91]
	v_mfma_f32_16x16x32_bf16 v[76:79], v[14:17], v[198:201], v[76:79]
	v_mfma_f32_16x16x32_bf16 v[72:75], v[22:25], v[198:201], v[72:75]
	v_mfma_f32_16x16x32_bf16 v[60:63], v[14:17], v[220:223], v[60:63]
	v_mfma_f32_16x16x32_bf16 v[56:59], v[22:25], v[220:223], v[56:59]
	v_mfma_f32_16x16x32_bf16 v[14:17], v[14:17], v[228:231], v[44:47]
	v_mfma_f32_16x16x32_bf16 v[92:95], v[18:21], v[194:197], v[92:95]
	v_mfma_f32_16x16x32_bf16 v[88:91], v[26:29], v[194:197], v[88:91]
	v_mfma_f32_16x16x32_bf16 v[76:79], v[18:21], v[202:205], v[76:79]
	v_mfma_f32_16x16x32_bf16 v[72:75], v[26:29], v[202:205], v[72:75]
	v_mfma_f32_16x16x32_bf16 v[60:63], v[18:21], v[224:227], v[60:63]
	v_mfma_f32_16x16x32_bf16 v[56:59], v[26:29], v[224:227], v[56:59]
	v_mfma_f32_16x16x32_bf16 v[14:17], v[18:21], v[232:235], v[14:17]
	v_mfma_f32_16x16x32_bf16 v[18:21], v[22:25], v[228:231], v[40:43]
	v_mfma_f32_16x16x32_bf16 v[18:21], v[26:29], v[232:235], v[18:21]
	s_setprio 0
	s_setprio 1
	v_mfma_f32_16x16x32_bf16 v[40:43], v[160:163], v[198:201], v[68:71]
	v_mfma_f32_16x16x32_bf16 v[68:71], v[164:167], v[202:205], v[40:43]
	v_mfma_f32_16x16x32_bf16 v[40:43], v[168:171], v[198:201], v[64:67]
	v_mfma_f32_16x16x32_bf16 v[64:67], v[172:175], v[202:205], v[40:43]
	v_mfma_f32_16x16x32_bf16 v[40:43], v[160:163], v[220:223], v[52:55]
	v_mfma_f32_16x16x32_bf16 v[52:55], v[164:167], v[224:227], v[40:43]
	v_mfma_f32_16x16x32_bf16 v[40:43], v[168:171], v[220:223], v[48:51]
	v_mfma_f32_16x16x32_bf16 v[36:39], v[160:163], v[228:231], v[36:39]
	v_mfma_f32_16x16x32_bf16 v[30:33], v[168:171], v[228:231], v[32:35]
	v_mfma_f32_16x16x32_bf16 v[22:25], v[160:163], v[186:189], v[84:87]
	v_mfma_f32_16x16x32_bf16 v[26:29], v[168:171], v[186:189], v[80:83]
	v_mfma_f32_16x16x32_bf16 v[48:51], v[172:175], v[224:227], v[40:43]
	v_mfma_f32_16x16x32_bf16 v[36:39], v[164:167], v[232:235], v[36:39]
	v_mfma_f32_16x16x32_bf16 v[30:33], v[172:175], v[232:235], v[30:33]
	v_mfma_f32_16x16x32_bf16 v[22:25], v[164:167], v[194:197], v[22:25]
	v_mfma_f32_16x16x32_bf16 v[26:29], v[172:175], v[194:197], v[26:29]
	s_setprio 0
	s_barrier
	v_or_b32_e32 v13, 0x18000, v12
	v_add_u32_e32 v34, 0x18400, v12
	ds_read_b128 v[40:43], v13
	ds_read_b128 v[44:47], v34
	v_add_u32_e32 v13, 0x18800, v12
	v_add_u32_e32 v34, 0x18c00, v12
	ds_read_b128 v[80:83], v13
	ds_read_b128 v[84:87], v34
	v_or_b32_e32 v13, 0x1c000, v12
	v_add_u32_e32 v34, 0x1c400, v12
	ds_read_b128 v[160:163], v13
	ds_read_b128 v[164:167], v34
	v_add_u32_e32 v13, 0x1c800, v12
	v_add_u32_e32 v34, 0x1cc00, v12
	ds_read_b128 v[168:171], v13
	ds_read_b128 v[172:175], v34
	s_add_u32 s6, s6, 0x40000
	s_addc_u32 s7, s7, 0
	s_mov_b32 m0, s28
	v_lshl_add_u64 v[34:35], s[6:7], 0, v[176:177]
	ds_read_b128 v[186:189], v11 offset:32768
	ds_read_b128 v[194:197], v11 offset:33792
	ds_read_b128 v[198:201], v11 offset:34816
	ds_read_b128 v[202:205], v11 offset:35840
	ds_read_b128 v[220:223], v11 offset:36864
	ds_read_b128 v[224:227], v11 offset:37888
	ds_read_b128 v[228:231], v11 offset:38912
	ds_read_b128 v[232:235], v11 offset:39936
	global_load_lds_dwordx4 v[34:35], off
	v_lshl_add_u64 v[34:35], s[6:7], 0, v[0:1]
	s_mov_b32 m0, s29
	s_nop 0
	global_load_lds_dwordx4 v[34:35], off
	s_waitcnt vmcnt(8)
	s_waitcnt lgkmcnt(0)
	s_barrier
	s_setprio 1
	s_waitcnt lgkmcnt(0)
	v_mfma_f32_16x16x32_bf16 v[156:159], v[40:43], v[186:189], v[156:159]
	v_mfma_f32_16x16x32_bf16 v[152:155], v[80:83], v[186:189], v[152:155]
	v_mfma_f32_16x16x32_bf16 v[140:143], v[40:43], v[198:201], v[140:143]
	v_mfma_f32_16x16x32_bf16 v[136:139], v[80:83], v[198:201], v[136:139]
	v_mfma_f32_16x16x32_bf16 v[124:127], v[40:43], v[220:223], v[124:127]
	v_mfma_f32_16x16x32_bf16 v[120:123], v[80:83], v[220:223], v[120:123]
	v_mfma_f32_16x16x32_bf16 v[108:111], v[40:43], v[228:231], v[108:111]
	v_mfma_f32_16x16x32_bf16 v[104:107], v[80:83], v[228:231], v[104:107]
	v_mfma_f32_16x16x32_bf16 v[156:159], v[44:47], v[194:197], v[156:159]
	v_mfma_f32_16x16x32_bf16 v[152:155], v[84:87], v[194:197], v[152:155]
	v_mfma_f32_16x16x32_bf16 v[140:143], v[44:47], v[202:205], v[140:143]
	v_mfma_f32_16x16x32_bf16 v[136:139], v[84:87], v[202:205], v[136:139]
	v_mfma_f32_16x16x32_bf16 v[124:127], v[44:47], v[224:227], v[124:127]
	v_mfma_f32_16x16x32_bf16 v[120:123], v[84:87], v[224:227], v[120:123]
	v_mfma_f32_16x16x32_bf16 v[108:111], v[44:47], v[232:235], v[108:111]
	v_mfma_f32_16x16x32_bf16 v[104:107], v[84:87], v[232:235], v[104:107]
	s_setprio 0
	s_setprio 1
	v_mfma_f32_16x16x32_bf16 v[148:151], v[160:163], v[186:189], v[148:151]
	v_mfma_f32_16x16x32_bf16 v[144:147], v[168:171], v[186:189], v[144:147]
	v_mfma_f32_16x16x32_bf16 v[132:135], v[160:163], v[198:201], v[132:135]
	v_mfma_f32_16x16x32_bf16 v[128:131], v[168:171], v[198:201], v[128:131]
	v_mfma_f32_16x16x32_bf16 v[116:119], v[160:163], v[220:223], v[116:119]
	v_mfma_f32_16x16x32_bf16 v[112:115], v[168:171], v[220:223], v[112:115]
	v_mfma_f32_16x16x32_bf16 v[100:103], v[160:163], v[228:231], v[100:103]
	v_mfma_f32_16x16x32_bf16 v[96:99], v[168:171], v[228:231], v[96:99]
	v_mfma_f32_16x16x32_bf16 v[148:151], v[164:167], v[194:197], v[148:151]
	v_mfma_f32_16x16x32_bf16 v[144:147], v[172:175], v[194:197], v[144:147]
	v_mfma_f32_16x16x32_bf16 v[132:135], v[164:167], v[202:205], v[132:135]
	v_mfma_f32_16x16x32_bf16 v[128:131], v[172:175], v[202:205], v[128:131]
	v_mfma_f32_16x16x32_bf16 v[116:119], v[164:167], v[224:227], v[116:119]
	v_mfma_f32_16x16x32_bf16 v[112:115], v[172:175], v[224:227], v[112:115]
	v_mfma_f32_16x16x32_bf16 v[100:103], v[164:167], v[232:235], v[100:103]
	v_mfma_f32_16x16x32_bf16 v[96:99], v[172:175], v[232:235], v[96:99]
	s_setprio 0
	s_barrier
	s_mov_b32 m0, s30
	v_lshl_add_u64 v[34:35], v[190:191], 0, s[0:1]
	s_add_u32 s2, s2, 0x40080
	ds_read_b128 v[186:189], v11 offset:49152
	ds_read_b128 v[194:197], v11 offset:50176
	ds_read_b128 v[198:201], v11 offset:51200
	ds_read_b128 v[202:205], v11 offset:52224
	ds_read_b128 v[220:223], v11 offset:53248
	ds_read_b128 v[224:227], v11 offset:54272
	ds_read_b128 v[228:231], v11 offset:55296
	ds_read_b128 v[232:235], v11 offset:56320
	global_load_lds_dwordx4 v[34:35], off
	v_lshl_add_u64 v[34:35], v[214:215], 0, s[0:1]
	s_mov_b32 m0, s31
	s_addc_u32 s3, s3, 0
	global_load_lds_dwordx4 v[34:35], off
	v_lshl_add_u64 v[34:35], s[2:3], 0, v[176:177]
	s_mov_b32 m0, s42
	s_nop 0
	global_load_lds_dwordx4 v[34:35], off
	v_lshl_add_u64 v[34:35], s[2:3], 0, v[0:1]
	s_mov_b32 m0, s43
	s_nop 0
	global_load_lds_dwordx4 v[34:35], off
	v_lshl_add_u64 v[34:35], v[236:237], 0, s[0:1]
	s_mov_b32 m0, s34
	s_nop 0
	global_load_lds_dwordx4 v[34:35], off
	v_lshl_add_u64 v[34:35], v[238:239], 0, s[0:1]
	s_mov_b32 m0, s35
	s_nop 0
	global_load_lds_dwordx4 v[34:35], off
	s_waitcnt vmcnt(8)
	s_waitcnt lgkmcnt(0)
	s_barrier
	s_setprio 1
	s_waitcnt lgkmcnt(0)
	v_mfma_f32_16x16x32_bf16 v[92:95], v[40:43], v[186:189], v[92:95]
	v_mfma_f32_16x16x32_bf16 v[76:79], v[40:43], v[198:201], v[76:79]
	v_mfma_f32_16x16x32_bf16 v[60:63], v[40:43], v[220:223], v[60:63]
	v_mfma_f32_16x16x32_bf16 v[14:17], v[40:43], v[228:231], v[14:17]
	v_mfma_f32_16x16x32_bf16 v[92:95], v[44:47], v[194:197], v[92:95]
	v_mfma_f32_16x16x32_bf16 v[88:91], v[80:83], v[186:189], v[88:91]
	v_mfma_f32_16x16x32_bf16 v[76:79], v[44:47], v[202:205], v[76:79]
	v_mfma_f32_16x16x32_bf16 v[72:75], v[80:83], v[198:201], v[72:75]
	v_mfma_f32_16x16x32_bf16 v[60:63], v[44:47], v[224:227], v[60:63]
	v_mfma_f32_16x16x32_bf16 v[56:59], v[80:83], v[220:223], v[56:59]
	v_mfma_f32_16x16x32_bf16 v[44:47], v[44:47], v[232:235], v[14:17]
	v_mfma_f32_16x16x32_bf16 v[14:17], v[80:83], v[228:231], v[18:21]
	v_mfma_f32_16x16x32_bf16 v[88:91], v[84:87], v[194:197], v[88:91]
	v_mfma_f32_16x16x32_bf16 v[72:75], v[84:87], v[202:205], v[72:75]
	v_mfma_f32_16x16x32_bf16 v[56:59], v[84:87], v[224:227], v[56:59]
	v_mfma_f32_16x16x32_bf16 v[40:43], v[84:87], v[232:235], v[14:17]
	s_setprio 0
	s_setprio 1
	v_mfma_f32_16x16x32_bf16 v[14:17], v[160:163], v[186:189], v[22:25]
	v_mfma_f32_16x16x32_bf16 v[84:87], v[164:167], v[194:197], v[14:17]
	v_mfma_f32_16x16x32_bf16 v[14:17], v[168:171], v[186:189], v[26:29]
	v_mfma_f32_16x16x32_bf16 v[80:83], v[172:175], v[194:197], v[14:17]
	v_mfma_f32_16x16x32_bf16 v[14:17], v[160:163], v[198:201], v[68:71]
	v_mfma_f32_16x16x32_bf16 v[68:71], v[164:167], v[202:205], v[14:17]
	v_mfma_f32_16x16x32_bf16 v[14:17], v[168:171], v[198:201], v[64:67]
	v_mfma_f32_16x16x32_bf16 v[64:67], v[172:175], v[202:205], v[14:17]
	v_mfma_f32_16x16x32_bf16 v[14:17], v[160:163], v[220:223], v[52:55]
	v_mfma_f32_16x16x32_bf16 v[52:55], v[164:167], v[224:227], v[14:17]
	v_mfma_f32_16x16x32_bf16 v[14:17], v[168:171], v[220:223], v[48:51]
	v_mfma_f32_16x16x32_bf16 v[48:51], v[172:175], v[224:227], v[14:17]
	v_mfma_f32_16x16x32_bf16 v[14:17], v[160:163], v[228:231], v[36:39]
	v_mfma_f32_16x16x32_bf16 v[36:39], v[164:167], v[232:235], v[14:17]
	v_mfma_f32_16x16x32_bf16 v[14:17], v[168:171], v[228:231], v[30:33]
	v_mfma_f32_16x16x32_bf16 v[32:35], v[172:175], v[232:235], v[14:17]
	s_setprio 0
	s_barrier
	s_add_i32 s95, s95, 2
	s_add_u32 s90, s90, 0x100
	s_addc_u32 s91, s91, 0
	s_cmp_gt_u32 s95, 13
	s_cbranch_scc0 .LBB0_326
	s_add_u32 s2, s75, 0xffffff00
	s_addc_u32 s3, s83, -1
	s_andn2_b64 vcc, exec, s[38:39]
	s_cbranch_vccnz .LBB0_317
	v_mov_b32_e32 v32, 0
	s_mov_b32 s9, s4
	s_mov_b32 s82, s84
	s_mov_b64 s[40:41], s[88:89]
	s_mov_b32 s72, s74
	v_mov_b32_e32 v33, v32
	v_mov_b32_e32 v34, v32
	v_mov_b32_e32 v35, v32
	v_mov_b32_e32 v36, v32
	v_mov_b32_e32 v37, v32
	v_mov_b32_e32 v38, v32
	v_mov_b32_e32 v39, v32
	v_mov_b32_e32 v48, v32
	v_mov_b32_e32 v49, v32
	v_mov_b32_e32 v50, v32
	v_mov_b32_e32 v51, v32
	v_mov_b32_e32 v52, v32
	v_mov_b32_e32 v53, v32
	v_mov_b32_e32 v54, v32
	v_mov_b32_e32 v55, v32
	v_mov_b32_e32 v64, v32
	v_mov_b32_e32 v65, v32
	v_mov_b32_e32 v66, v32
	v_mov_b32_e32 v67, v32
	v_mov_b32_e32 v68, v32
	v_mov_b32_e32 v69, v32
	v_mov_b32_e32 v70, v32
	v_mov_b32_e32 v71, v32
	v_mov_b32_e32 v80, v32
	v_mov_b32_e32 v81, v32
	v_mov_b32_e32 v82, v32
	v_mov_b32_e32 v83, v32
	v_mov_b32_e32 v84, v32
	v_mov_b32_e32 v85, v32
	v_mov_b32_e32 v86, v32
	v_mov_b32_e32 v87, v32
	v_mov_b32_e32 v40, v32
	v_mov_b32_e32 v41, v32
	v_mov_b32_e32 v42, v32
	v_mov_b32_e32 v43, v32
	v_mov_b32_e32 v44, v32
	v_mov_b32_e32 v45, v32
	v_mov_b32_e32 v46, v32
	v_mov_b32_e32 v47, v32
	v_mov_b32_e32 v56, v32
	v_mov_b32_e32 v57, v32
	v_mov_b32_e32 v58, v32
	v_mov_b32_e32 v59, v32
	v_mov_b32_e32 v60, v32
	v_mov_b32_e32 v61, v32
	v_mov_b32_e32 v62, v32
	v_mov_b32_e32 v63, v32
	v_mov_b32_e32 v72, v32
	v_mov_b32_e32 v73, v32
	v_mov_b32_e32 v74, v32
	v_mov_b32_e32 v75, v32
	v_mov_b32_e32 v76, v32
	v_mov_b32_e32 v77, v32
	v_mov_b32_e32 v78, v32
	v_mov_b32_e32 v79, v32
	v_mov_b32_e32 v88, v32
	v_mov_b32_e32 v89, v32
	v_mov_b32_e32 v90, v32
	v_mov_b32_e32 v91, v32
	v_mov_b32_e32 v92, v32
	v_mov_b32_e32 v93, v32
	v_mov_b32_e32 v94, v32
	v_mov_b32_e32 v95, v32
	v_mov_b32_e32 v96, v32
	v_mov_b32_e32 v97, v32
	v_mov_b32_e32 v98, v32
	v_mov_b32_e32 v99, v32
	v_mov_b32_e32 v100, v32
	v_mov_b32_e32 v101, v32
	v_mov_b32_e32 v102, v32
	v_mov_b32_e32 v103, v32
	v_mov_b32_e32 v112, v32
	v_mov_b32_e32 v113, v32
	v_mov_b32_e32 v114, v32
	v_mov_b32_e32 v115, v32
	v_mov_b32_e32 v116, v32
	v_mov_b32_e32 v117, v32
	v_mov_b32_e32 v118, v32
	v_mov_b32_e32 v119, v32
	v_mov_b32_e32 v128, v32
	v_mov_b32_e32 v129, v32
	v_mov_b32_e32 v130, v32
	v_mov_b32_e32 v131, v32
	v_mov_b32_e32 v132, v32
	v_mov_b32_e32 v133, v32
	v_mov_b32_e32 v134, v32
	v_mov_b32_e32 v135, v32
	v_mov_b32_e32 v144, v32
	v_mov_b32_e32 v145, v32
	v_mov_b32_e32 v146, v32
	v_mov_b32_e32 v147, v32
	v_mov_b32_e32 v148, v32
	v_mov_b32_e32 v149, v32
	v_mov_b32_e32 v150, v32
	v_mov_b32_e32 v151, v32
	v_mov_b32_e32 v104, v32
	v_mov_b32_e32 v105, v32
	v_mov_b32_e32 v106, v32
	v_mov_b32_e32 v107, v32
	v_mov_b32_e32 v108, v32
	v_mov_b32_e32 v109, v32
	v_mov_b32_e32 v110, v32
	v_mov_b32_e32 v111, v32
	v_mov_b32_e32 v120, v32
	v_mov_b32_e32 v121, v32
	v_mov_b32_e32 v122, v32
	v_mov_b32_e32 v123, v32
	v_mov_b32_e32 v124, v32
	v_mov_b32_e32 v125, v32
	v_mov_b32_e32 v126, v32
	v_mov_b32_e32 v127, v32
	v_mov_b32_e32 v136, v32
	v_mov_b32_e32 v137, v32
	v_mov_b32_e32 v138, v32
	v_mov_b32_e32 v139, v32
	v_mov_b32_e32 v140, v32
	v_mov_b32_e32 v141, v32
	v_mov_b32_e32 v142, v32
	v_mov_b32_e32 v143, v32
	v_mov_b32_e32 v152, v32
	v_mov_b32_e32 v153, v32
	v_mov_b32_e32 v154, v32
	v_mov_b32_e32 v155, v32
	v_mov_b32_e32 v156, v32
	v_mov_b32_e32 v157, v32
	v_mov_b32_e32 v158, v32
	v_mov_b32_e32 v159, v32
	s_andn2_b64 vcc, exec, s[36:37]
	s_cbranch_vccnz .LBB0_318

.LBB0_438:
	v_or_b32_e32 v143, 0x10000, v140
	v_add_u32_e32 v148, 0x10400, v140
	ds_read_b128 v[144:147], v143
	ds_read_b128 v[148:151], v148
	v_add_u32_e32 v143, 0x10800, v140
	v_add_u32_e32 v156, 0x10c00, v140
	ds_read_b128 v[152:155], v143
	ds_read_b128 v[156:159], v156
	v_or_b32_e32 v143, 0x14000, v140
	v_add_u32_e32 v164, 0x14400, v140
	ds_read_b128 v[160:163], v143
	ds_read_b128 v[164:167], v164
	v_add_u32_e32 v143, 0x14800, v140
	v_add_u32_e32 v172, 0x14c00, v140
	ds_read_b128 v[168:171], v143
	ds_read_b128 v[172:175], v172
	s_add_u32 s2, s90, 0xfffc0080
	s_addc_u32 s3, s91, -1
	s_cmp_eq_u32 s95, 12
	s_cselect_b32 s7, s8, s3
	s_cselect_b32 s6, s9, s2
	s_cselect_b32 s3, s83, s94
	s_cselect_b32 s2, s85, s92
	v_lshl_add_u64 v[232:233], s[90:91], 0, v[134:135]
	s_add_i32 m0, s20, 0xc000
	ds_read_b128 v[186:189], v139
	ds_read_b128 v[190:193], v139 offset:1024
	ds_read_b128 v[194:197], v139 offset:2048
	ds_read_b128 v[198:201], v139 offset:3072
	ds_read_b128 v[202:205], v139 offset:4096
	ds_read_b128 v[220:223], v139 offset:5120
	ds_read_b128 v[224:227], v139 offset:6144
	ds_read_b128 v[228:231], v139 offset:7168
	global_load_lds_dwordx4 v[232:233], off
	v_lshl_add_u64 v[232:233], s[90:91], 0, v[136:137]
	s_add_i32 m0, s20, 0xe000
	s_nop 0
	global_load_lds_dwordx4 v[232:233], off
	s_waitcnt vmcnt(8)
	s_waitcnt lgkmcnt(0)
	s_barrier
	s_setprio 1
	s_waitcnt lgkmcnt(0)
	v_mfma_f32_16x16x32_bf16 v[124:127], v[144:147], v[186:189], v[124:127]
	v_mfma_f32_16x16x32_bf16 v[120:123], v[152:155], v[186:189], v[120:123]
	v_mfma_f32_16x16x32_bf16 v[116:119], v[144:147], v[194:197], v[116:119]
	v_mfma_f32_16x16x32_bf16 v[112:115], v[152:155], v[194:197], v[112:115]
	v_mfma_f32_16x16x32_bf16 v[100:103], v[144:147], v[202:205], v[100:103]
	v_mfma_f32_16x16x32_bf16 v[96:99], v[152:155], v[202:205], v[96:99]
	v_mfma_f32_16x16x32_bf16 v[84:87], v[144:147], v[224:227], v[84:87]
	v_mfma_f32_16x16x32_bf16 v[80:83], v[152:155], v[224:227], v[80:83]
	v_mfma_f32_16x16x32_bf16 v[124:127], v[148:151], v[190:193], v[124:127]
	v_mfma_f32_16x16x32_bf16 v[120:123], v[156:159], v[190:193], v[120:123]
	v_mfma_f32_16x16x32_bf16 v[116:119], v[148:151], v[198:201], v[116:119]
	v_mfma_f32_16x16x32_bf16 v[112:115], v[156:159], v[198:201], v[112:115]
	v_mfma_f32_16x16x32_bf16 v[100:103], v[148:151], v[220:223], v[100:103]
	v_mfma_f32_16x16x32_bf16 v[96:99], v[156:159], v[220:223], v[96:99]
	v_mfma_f32_16x16x32_bf16 v[84:87], v[148:151], v[228:231], v[84:87]
	v_mfma_f32_16x16x32_bf16 v[80:83], v[156:159], v[228:231], v[80:83]
	s_setprio 0
	s_setprio 1
	v_mfma_f32_16x16x32_bf16 v[108:111], v[160:163], v[186:189], v[108:111]
	v_mfma_f32_16x16x32_bf16 v[104:107], v[168:171], v[186:189], v[104:107]
	v_mfma_f32_16x16x32_bf16 v[92:95], v[160:163], v[194:197], v[92:95]
	v_mfma_f32_16x16x32_bf16 v[88:91], v[168:171], v[194:197], v[88:91]
	v_mfma_f32_16x16x32_bf16 v[76:79], v[160:163], v[202:205], v[76:79]
	v_mfma_f32_16x16x32_bf16 v[72:75], v[168:171], v[202:205], v[72:75]
	v_mfma_f32_16x16x32_bf16 v[68:71], v[160:163], v[224:227], v[68:71]
	v_mfma_f32_16x16x32_bf16 v[64:67], v[168:171], v[224:227], v[64:67]
	v_mfma_f32_16x16x32_bf16 v[108:111], v[164:167], v[190:193], v[108:111]
	v_mfma_f32_16x16x32_bf16 v[104:107], v[172:175], v[190:193], v[104:107]
	v_mfma_f32_16x16x32_bf16 v[92:95], v[164:167], v[198:201], v[92:95]
	v_mfma_f32_16x16x32_bf16 v[88:91], v[172:175], v[198:201], v[88:91]
	v_mfma_f32_16x16x32_bf16 v[76:79], v[164:167], v[220:223], v[76:79]
	v_mfma_f32_16x16x32_bf16 v[72:75], v[172:175], v[220:223], v[72:75]
	v_mfma_f32_16x16x32_bf16 v[68:71], v[164:167], v[228:231], v[68:71]
	v_mfma_f32_16x16x32_bf16 v[64:67], v[172:175], v[228:231], v[64:67]
	s_setprio 0
	s_barrier
	s_mov_b32 m0, s5
	v_lshl_add_u64 v[232:233], s[2:3], 0, v[176:177]
	s_add_u32 s96, s2, 0x40000
	ds_read_b128 v[186:189], v139 offset:16384
	ds_read_b128 v[190:193], v139 offset:17408
	ds_read_b128 v[194:197], v139 offset:18432
	ds_read_b128 v[198:201], v139 offset:19456
	ds_read_b128 v[202:205], v139 offset:20480
	ds_read_b128 v[220:223], v139 offset:21504
	ds_read_b128 v[224:227], v139 offset:22528
	ds_read_b128 v[228:231], v139 offset:23552
	global_load_lds_dwordx4 v[232:233], off
	v_lshl_add_u64 v[234:235], s[2:3], 0, v[128:129]
	s_mov_b32 m0, s22
	s_addc_u32 s97, s3, 0
	global_load_lds_dwordx4 v[234:235], off
	v_lshl_add_u64 v[236:237], s[96:97], 0, v[176:177]
	s_mov_b32 m0, s23
	v_lshl_add_u64 v[238:239], s[6:7], 0, v[130:131]
	global_load_lds_dwordx4 v[236:237], off
	v_lshl_add_u64 v[236:237], s[96:97], 0, v[128:129]
	s_mov_b32 m0, s24
	s_nop 0
	global_load_lds_dwordx4 v[236:237], off
	v_lshl_add_u64 v[236:237], s[6:7], 0, v[132:133]
	s_mov_b32 m0, s20
	s_nop 0
	global_load_lds_dwordx4 v[236:237], off
	s_mov_b32 m0, s25
	s_nop 0
	global_load_lds_dwordx4 v[238:239], off
	s_waitcnt vmcnt(8)
	s_waitcnt lgkmcnt(0)
	s_barrier
	s_setprio 1
	s_waitcnt lgkmcnt(0)
	v_mfma_f32_16x16x32_bf16 v[60:63], v[144:147], v[186:189], v[60:63]
	v_mfma_f32_16x16x32_bf16 v[56:59], v[152:155], v[186:189], v[56:59]
	v_mfma_f32_16x16x32_bf16 v[52:55], v[144:147], v[194:197], v[52:55]
	v_mfma_f32_16x16x32_bf16 v[48:51], v[152:155], v[194:197], v[48:51]
	v_mfma_f32_16x16x32_bf16 v[36:39], v[144:147], v[202:205], v[36:39]
	v_mfma_f32_16x16x32_bf16 v[32:35], v[152:155], v[202:205], v[32:35]
	v_mfma_f32_16x16x32_bf16 v[20:23], v[144:147], v[224:227], v[20:23]
	v_mfma_f32_16x16x32_bf16 v[16:19], v[152:155], v[224:227], v[16:19]
	v_mfma_f32_16x16x32_bf16 v[60:63], v[148:151], v[190:193], v[60:63]
	v_mfma_f32_16x16x32_bf16 v[56:59], v[156:159], v[190:193], v[56:59]
	v_mfma_f32_16x16x32_bf16 v[52:55], v[148:151], v[198:201], v[52:55]
	v_mfma_f32_16x16x32_bf16 v[48:51], v[156:159], v[198:201], v[48:51]
	v_mfma_f32_16x16x32_bf16 v[36:39], v[148:151], v[220:223], v[36:39]
	v_mfma_f32_16x16x32_bf16 v[32:35], v[156:159], v[220:223], v[32:35]
	v_mfma_f32_16x16x32_bf16 v[20:23], v[148:151], v[228:231], v[20:23]
	v_mfma_f32_16x16x32_bf16 v[16:19], v[156:159], v[228:231], v[16:19]
	s_setprio 0
	s_setprio 1
	v_mfma_f32_16x16x32_bf16 v[44:47], v[160:163], v[186:189], v[44:47]
	v_mfma_f32_16x16x32_bf16 v[40:43], v[168:171], v[186:189], v[40:43]
	v_mfma_f32_16x16x32_bf16 v[28:31], v[160:163], v[194:197], v[28:31]
	v_mfma_f32_16x16x32_bf16 v[24:27], v[168:171], v[194:197], v[24:27]
	v_mfma_f32_16x16x32_bf16 v[12:15], v[160:163], v[202:205], v[12:15]
	v_mfma_f32_16x16x32_bf16 v[8:11], v[168:171], v[202:205], v[8:11]
	v_mfma_f32_16x16x32_bf16 v[4:7], v[160:163], v[224:227], v[4:7]
	v_mfma_f32_16x16x32_bf16 v[0:3], v[168:171], v[224:227], v[0:3]
	v_mfma_f32_16x16x32_bf16 v[44:47], v[164:167], v[190:193], v[44:47]
	v_mfma_f32_16x16x32_bf16 v[40:43], v[172:175], v[190:193], v[40:43]
	v_mfma_f32_16x16x32_bf16 v[28:31], v[164:167], v[198:201], v[28:31]
	v_mfma_f32_16x16x32_bf16 v[24:27], v[172:175], v[198:201], v[24:27]
	v_mfma_f32_16x16x32_bf16 v[12:15], v[164:167], v[220:223], v[12:15]
	v_mfma_f32_16x16x32_bf16 v[8:11], v[172:175], v[220:223], v[8:11]
	v_mfma_f32_16x16x32_bf16 v[4:7], v[164:167], v[228:231], v[4:7]
	v_mfma_f32_16x16x32_bf16 v[0:3], v[172:175], v[228:231], v[0:3]
	s_setprio 0
	s_barrier
	v_or_b32_e32 v143, 0x18000, v140
	v_add_u32_e32 v148, 0x18400, v140
	ds_read_b128 v[144:147], v143
	ds_read_b128 v[148:151], v148
	v_add_u32_e32 v143, 0x18800, v140
	v_add_u32_e32 v156, 0x18c00, v140
	ds_read_b128 v[152:155], v143
	ds_read_b128 v[156:159], v156
	v_or_b32_e32 v143, 0x1c000, v140
	v_add_u32_e32 v164, 0x1c400, v140
	ds_read_b128 v[160:163], v143
	ds_read_b128 v[164:167], v164
	v_add_u32_e32 v143, 0x1c800, v140
	v_add_u32_e32 v172, 0x1cc00, v140
	ds_read_b128 v[168:171], v143
	ds_read_b128 v[172:175], v172
	s_add_u32 s6, s6, 0x40000
	s_addc_u32 s7, s7, 0
	s_mov_b32 m0, s26
	v_lshl_add_u64 v[240:241], s[6:7], 0, v[132:133]
	ds_read_b128 v[186:189], v139 offset:32768
	ds_read_b128 v[190:193], v139 offset:33792
	ds_read_b128 v[194:197], v139 offset:34816
	ds_read_b128 v[198:201], v139 offset:35840
	ds_read_b128 v[202:205], v139 offset:36864
	ds_read_b128 v[220:223], v139 offset:37888
	ds_read_b128 v[224:227], v139 offset:38912
	ds_read_b128 v[228:231], v139 offset:39936
	global_load_lds_dwordx4 v[240:241], off
	v_lshl_add_u64 v[240:241], s[6:7], 0, v[130:131]
	s_mov_b32 m0, s27
	s_nop 0
	global_load_lds_dwordx4 v[240:241], off
	s_waitcnt vmcnt(8)
	s_waitcnt lgkmcnt(0)
	s_barrier
	s_setprio 1
	s_waitcnt lgkmcnt(0)
	v_mfma_f32_16x16x32_bf16 v[124:127], v[144:147], v[186:189], v[124:127]
	v_mfma_f32_16x16x32_bf16 v[120:123], v[152:155], v[186:189], v[120:123]
	v_mfma_f32_16x16x32_bf16 v[116:119], v[144:147], v[194:197], v[116:119]
	v_mfma_f32_16x16x32_bf16 v[112:115], v[152:155], v[194:197], v[112:115]
	v_mfma_f32_16x16x32_bf16 v[100:103], v[144:147], v[202:205], v[100:103]
	v_mfma_f32_16x16x32_bf16 v[96:99], v[152:155], v[202:205], v[96:99]
	v_mfma_f32_16x16x32_bf16 v[84:87], v[144:147], v[224:227], v[84:87]
	v_mfma_f32_16x16x32_bf16 v[80:83], v[152:155], v[224:227], v[80:83]
	v_mfma_f32_16x16x32_bf16 v[124:127], v[148:151], v[190:193], v[124:127]
	v_mfma_f32_16x16x32_bf16 v[120:123], v[156:159], v[190:193], v[120:123]
	v_mfma_f32_16x16x32_bf16 v[116:119], v[148:151], v[198:201], v[116:119]
	v_mfma_f32_16x16x32_bf16 v[112:115], v[156:159], v[198:201], v[112:115]
	v_mfma_f32_16x16x32_bf16 v[100:103], v[148:151], v[220:223], v[100:103]
	v_mfma_f32_16x16x32_bf16 v[96:99], v[156:159], v[220:223], v[96:99]
	v_mfma_f32_16x16x32_bf16 v[84:87], v[148:151], v[228:231], v[84:87]
	v_mfma_f32_16x16x32_bf16 v[80:83], v[156:159], v[228:231], v[80:83]
	s_setprio 0
	s_setprio 1
	v_mfma_f32_16x16x32_bf16 v[108:111], v[160:163], v[186:189], v[108:111]
	v_mfma_f32_16x16x32_bf16 v[104:107], v[168:171], v[186:189], v[104:107]
	v_mfma_f32_16x16x32_bf16 v[92:95], v[160:163], v[194:197], v[92:95]
	v_mfma_f32_16x16x32_bf16 v[88:91], v[168:171], v[194:197], v[88:91]
	v_mfma_f32_16x16x32_bf16 v[76:79], v[160:163], v[202:205], v[76:79]
	v_mfma_f32_16x16x32_bf16 v[72:75], v[168:171], v[202:205], v[72:75]
	v_mfma_f32_16x16x32_bf16 v[68:71], v[160:163], v[224:227], v[68:71]
	v_mfma_f32_16x16x32_bf16 v[64:67], v[168:171], v[224:227], v[64:67]
	v_mfma_f32_16x16x32_bf16 v[108:111], v[164:167], v[190:193], v[108:111]
	v_mfma_f32_16x16x32_bf16 v[104:107], v[172:175], v[190:193], v[104:107]
	v_mfma_f32_16x16x32_bf16 v[92:95], v[164:167], v[198:201], v[92:95]
	v_mfma_f32_16x16x32_bf16 v[88:91], v[172:175], v[198:201], v[88:91]
	v_mfma_f32_16x16x32_bf16 v[76:79], v[164:167], v[220:223], v[76:79]
	v_mfma_f32_16x16x32_bf16 v[72:75], v[172:175], v[220:223], v[72:75]
	v_mfma_f32_16x16x32_bf16 v[68:71], v[164:167], v[228:231], v[68:71]
	v_mfma_f32_16x16x32_bf16 v[64:67], v[172:175], v[228:231], v[64:67]
	s_setprio 0
	s_barrier
	s_mov_b32 m0, s28
	v_lshl_add_u64 v[232:233], v[232:233], 0, s[0:1]
	s_add_u32 s2, s2, 0x40080
	ds_read_b128 v[186:189], v139 offset:49152
	ds_read_b128 v[190:193], v139 offset:50176
	ds_read_b128 v[194:197], v139 offset:51200
	ds_read_b128 v[198:201], v139 offset:52224
	ds_read_b128 v[202:205], v139 offset:53248
	ds_read_b128 v[220:223], v139 offset:54272
	ds_read_b128 v[224:227], v139 offset:55296
	ds_read_b128 v[228:231], v139 offset:56320
	global_load_lds_dwordx4 v[232:233], off
	v_lshl_add_u64 v[232:233], v[234:235], 0, s[0:1]
	s_mov_b32 m0, s29
	s_addc_u32 s3, s3, 0
	global_load_lds_dwordx4 v[232:233], off
	v_lshl_add_u64 v[232:233], s[2:3], 0, v[176:177]
	s_mov_b32 m0, s34
	s_nop 0
	global_load_lds_dwordx4 v[232:233], off
	v_lshl_add_u64 v[232:233], s[2:3], 0, v[128:129]
	s_mov_b32 m0, s35
	s_nop 0
	global_load_lds_dwordx4 v[232:233], off
	v_lshl_add_u64 v[232:233], v[236:237], 0, s[0:1]
	s_mov_b32 m0, s30
	s_nop 0
	global_load_lds_dwordx4 v[232:233], off
	v_lshl_add_u64 v[232:233], v[238:239], 0, s[0:1]
	s_mov_b32 m0, s31
	s_nop 0
	global_load_lds_dwordx4 v[232:233], off
	s_waitcnt vmcnt(8)
	s_waitcnt lgkmcnt(0)
	s_barrier
	s_setprio 1
	s_waitcnt lgkmcnt(0)
	v_mfma_f32_16x16x32_bf16 v[60:63], v[144:147], v[186:189], v[60:63]
	v_mfma_f32_16x16x32_bf16 v[56:59], v[152:155], v[186:189], v[56:59]
	v_mfma_f32_16x16x32_bf16 v[52:55], v[144:147], v[194:197], v[52:55]
	v_mfma_f32_16x16x32_bf16 v[48:51], v[152:155], v[194:197], v[48:51]
	v_mfma_f32_16x16x32_bf16 v[36:39], v[144:147], v[202:205], v[36:39]
	v_mfma_f32_16x16x32_bf16 v[32:35], v[152:155], v[202:205], v[32:35]
	v_mfma_f32_16x16x32_bf16 v[20:23], v[144:147], v[224:227], v[20:23]
	v_mfma_f32_16x16x32_bf16 v[16:19], v[152:155], v[224:227], v[16:19]
	v_mfma_f32_16x16x32_bf16 v[60:63], v[148:151], v[190:193], v[60:63]
	v_mfma_f32_16x16x32_bf16 v[56:59], v[156:159], v[190:193], v[56:59]
	v_mfma_f32_16x16x32_bf16 v[52:55], v[148:151], v[198:201], v[52:55]
	v_mfma_f32_16x16x32_bf16 v[48:51], v[156:159], v[198:201], v[48:51]
	v_mfma_f32_16x16x32_bf16 v[36:39], v[148:151], v[220:223], v[36:39]
	v_mfma_f32_16x16x32_bf16 v[32:35], v[156:159], v[220:223], v[32:35]
	v_mfma_f32_16x16x32_bf16 v[20:23], v[148:151], v[228:231], v[20:23]
	v_mfma_f32_16x16x32_bf16 v[16:19], v[156:159], v[228:231], v[16:19]
	s_setprio 0
	s_setprio 1
	v_mfma_f32_16x16x32_bf16 v[44:47], v[160:163], v[186:189], v[44:47]
	v_mfma_f32_16x16x32_bf16 v[40:43], v[168:171], v[186:189], v[40:43]
	v_mfma_f32_16x16x32_bf16 v[28:31], v[160:163], v[194:197], v[28:31]
	v_mfma_f32_16x16x32_bf16 v[24:27], v[168:171], v[194:197], v[24:27]
	v_mfma_f32_16x16x32_bf16 v[12:15], v[160:163], v[202:205], v[12:15]
	v_mfma_f32_16x16x32_bf16 v[8:11], v[168:171], v[202:205], v[8:11]
	v_mfma_f32_16x16x32_bf16 v[4:7], v[160:163], v[224:227], v[4:7]
	v_mfma_f32_16x16x32_bf16 v[0:3], v[168:171], v[224:227], v[0:3]
	v_mfma_f32_16x16x32_bf16 v[44:47], v[164:167], v[190:193], v[44:47]
	v_mfma_f32_16x16x32_bf16 v[40:43], v[172:175], v[190:193], v[40:43]
	v_mfma_f32_16x16x32_bf16 v[28:31], v[164:167], v[198:201], v[28:31]
	v_mfma_f32_16x16x32_bf16 v[24:27], v[172:175], v[198:201], v[24:27]
	v_mfma_f32_16x16x32_bf16 v[12:15], v[164:167], v[220:223], v[12:15]
	v_mfma_f32_16x16x32_bf16 v[8:11], v[172:175], v[220:223], v[8:11]
	v_mfma_f32_16x16x32_bf16 v[4:7], v[164:167], v[228:231], v[4:7]
	v_mfma_f32_16x16x32_bf16 v[0:3], v[172:175], v[228:231], v[0:3]
	s_setprio 0
	s_barrier
	s_add_i32 s95, s95, 2
	s_add_u32 s90, s90, 0x100
	s_addc_u32 s91, s91, 0
	s_add_u32 s92, s92, 0x100
	s_addc_u32 s94, s94, 0
	s_cmp_gt_u32 s95, 13
	s_cbranch_scc0 .LBB0_438
	s_and_b64 vcc, exec, s[74:75]
	s_cbranch_vccz .LBB0_441
	s_barrier

.LBB0_462:
	v_or_b32_e32 v147, 0x10000, v145
	v_add_u32_e32 v152, 0x10400, v145
	ds_read_b128 v[148:151], v147
	ds_read_b128 v[152:155], v152
	v_add_u32_e32 v147, 0x10800, v145
	v_add_u32_e32 v160, 0x10c00, v145
	ds_read_b128 v[156:159], v147
	ds_read_b128 v[160:163], v160
	v_or_b32_e32 v147, 0x14000, v145
	v_add_u32_e32 v168, 0x14400, v145
	ds_read_b128 v[164:167], v147
	ds_read_b128 v[168:171], v168
	v_add_u32_e32 v147, 0x14800, v145
	v_add_u32_e32 v186, 0x14c00, v145
	ds_read_b128 v[172:175], v147
	ds_read_b128 v[186:189], v186
	s_add_u32 s2, s90, 0xfffc0080
	s_addc_u32 s3, s91, -1
	s_cmp_eq_u32 s95, 12
	s_cselect_b32 s7, s72, s3
	s_cselect_b32 s6, s75, s2
	s_cselect_b32 s3, s5, s94
	s_cselect_b32 s2, s85, s92
	v_lshl_add_u64 v[236:237], s[90:91], 0, v[138:139]
	s_add_i32 m0, s19, 0xc000
	ds_read_b128 v[190:193], v144
	ds_read_b128 v[194:197], v144 offset:1024
	ds_read_b128 v[198:201], v144 offset:2048
	ds_read_b128 v[202:205], v144 offset:3072
	ds_read_b128 v[220:223], v144 offset:4096
	ds_read_b128 v[224:227], v144 offset:5120
	ds_read_b128 v[228:231], v144 offset:6144
	ds_read_b128 v[232:235], v144 offset:7168
	global_load_lds_dwordx4 v[236:237], off
	v_lshl_add_u64 v[236:237], s[90:91], 0, v[140:141]
	s_add_i32 m0, s19, 0xe000
	s_nop 0
	global_load_lds_dwordx4 v[236:237], off
	s_waitcnt vmcnt(8)
	s_waitcnt lgkmcnt(0)
	s_barrier
	s_setprio 1
	s_waitcnt lgkmcnt(0)
	v_mfma_f32_16x16x32_bf16 v[124:127], v[148:151], v[190:193], v[124:127]
	v_mfma_f32_16x16x32_bf16 v[120:123], v[156:159], v[190:193], v[120:123]
	v_mfma_f32_16x16x32_bf16 v[116:119], v[148:151], v[198:201], v[116:119]
	v_mfma_f32_16x16x32_bf16 v[112:115], v[156:159], v[198:201], v[112:115]
	v_mfma_f32_16x16x32_bf16 v[100:103], v[148:151], v[220:223], v[100:103]
	v_mfma_f32_16x16x32_bf16 v[96:99], v[156:159], v[220:223], v[96:99]
	v_mfma_f32_16x16x32_bf16 v[84:87], v[148:151], v[228:231], v[84:87]
	v_mfma_f32_16x16x32_bf16 v[80:83], v[156:159], v[228:231], v[80:83]
	v_mfma_f32_16x16x32_bf16 v[124:127], v[152:155], v[194:197], v[124:127]
	v_mfma_f32_16x16x32_bf16 v[120:123], v[160:163], v[194:197], v[120:123]
	v_mfma_f32_16x16x32_bf16 v[116:119], v[152:155], v[202:205], v[116:119]
	v_mfma_f32_16x16x32_bf16 v[112:115], v[160:163], v[202:205], v[112:115]
	v_mfma_f32_16x16x32_bf16 v[100:103], v[152:155], v[224:227], v[100:103]
	v_mfma_f32_16x16x32_bf16 v[96:99], v[160:163], v[224:227], v[96:99]
	v_mfma_f32_16x16x32_bf16 v[84:87], v[152:155], v[232:235], v[84:87]
	v_mfma_f32_16x16x32_bf16 v[80:83], v[160:163], v[232:235], v[80:83]
	s_setprio 0
	s_setprio 1
	v_mfma_f32_16x16x32_bf16 v[108:111], v[164:167], v[190:193], v[108:111]
	v_mfma_f32_16x16x32_bf16 v[104:107], v[172:175], v[190:193], v[104:107]
	v_mfma_f32_16x16x32_bf16 v[92:95], v[164:167], v[198:201], v[92:95]
	v_mfma_f32_16x16x32_bf16 v[88:91], v[172:175], v[198:201], v[88:91]
	v_mfma_f32_16x16x32_bf16 v[76:79], v[164:167], v[220:223], v[76:79]
	v_mfma_f32_16x16x32_bf16 v[72:75], v[172:175], v[220:223], v[72:75]
	v_mfma_f32_16x16x32_bf16 v[68:71], v[164:167], v[228:231], v[68:71]
	v_mfma_f32_16x16x32_bf16 v[64:67], v[172:175], v[228:231], v[64:67]
	v_mfma_f32_16x16x32_bf16 v[108:111], v[168:171], v[194:197], v[108:111]
	v_mfma_f32_16x16x32_bf16 v[104:107], v[186:189], v[194:197], v[104:107]
	v_mfma_f32_16x16x32_bf16 v[92:95], v[168:171], v[202:205], v[92:95]
	v_mfma_f32_16x16x32_bf16 v[88:91], v[186:189], v[202:205], v[88:91]
	v_mfma_f32_16x16x32_bf16 v[76:79], v[168:171], v[224:227], v[76:79]
	v_mfma_f32_16x16x32_bf16 v[72:75], v[186:189], v[224:227], v[72:75]
	v_mfma_f32_16x16x32_bf16 v[68:71], v[168:171], v[232:235], v[68:71]
	v_mfma_f32_16x16x32_bf16 v[64:67], v[186:189], v[232:235], v[64:67]
	s_setprio 0
	s_barrier
	s_mov_b32 m0, s20
	v_lshl_add_u64 v[236:237], s[2:3], 0, v[130:131]
	s_add_u32 s96, s2, 0x40000
	ds_read_b128 v[190:193], v144 offset:16384
	ds_read_b128 v[194:197], v144 offset:17408
	ds_read_b128 v[198:201], v144 offset:18432
	ds_read_b128 v[202:205], v144 offset:19456
	ds_read_b128 v[220:223], v144 offset:20480
	ds_read_b128 v[224:227], v144 offset:21504
	ds_read_b128 v[228:231], v144 offset:22528
	ds_read_b128 v[232:235], v144 offset:23552
	global_load_lds_dwordx4 v[236:237], off
	v_lshl_add_u64 v[238:239], s[2:3], 0, v[134:135]
	s_mov_b32 m0, s21
	s_addc_u32 s97, s3, 0
	global_load_lds_dwordx4 v[238:239], off
	v_lshl_add_u64 v[240:241], s[96:97], 0, v[130:131]
	s_mov_b32 m0, s22
	v_lshl_add_u64 v[242:243], s[6:7], 0, v[132:133]
	global_load_lds_dwordx4 v[240:241], off
	v_lshl_add_u64 v[240:241], s[96:97], 0, v[134:135]
	s_mov_b32 m0, s23
	s_nop 0
	global_load_lds_dwordx4 v[240:241], off
	v_lshl_add_u64 v[240:241], s[6:7], 0, v[128:129]
	s_mov_b32 m0, s19
	s_nop 0
	global_load_lds_dwordx4 v[240:241], off
	s_mov_b32 m0, s24
	s_nop 0
	global_load_lds_dwordx4 v[242:243], off
	s_waitcnt vmcnt(8)
	s_waitcnt lgkmcnt(0)
	s_barrier
	s_setprio 1
	s_waitcnt lgkmcnt(0)
	v_mfma_f32_16x16x32_bf16 v[60:63], v[148:151], v[190:193], v[60:63]
	v_mfma_f32_16x16x32_bf16 v[56:59], v[156:159], v[190:193], v[56:59]
	v_mfma_f32_16x16x32_bf16 v[52:55], v[148:151], v[198:201], v[52:55]
	v_mfma_f32_16x16x32_bf16 v[48:51], v[156:159], v[198:201], v[48:51]
	v_mfma_f32_16x16x32_bf16 v[36:39], v[148:151], v[220:223], v[36:39]
	v_mfma_f32_16x16x32_bf16 v[32:35], v[156:159], v[220:223], v[32:35]
	v_mfma_f32_16x16x32_bf16 v[20:23], v[148:151], v[228:231], v[20:23]
	v_mfma_f32_16x16x32_bf16 v[16:19], v[156:159], v[228:231], v[16:19]
	v_mfma_f32_16x16x32_bf16 v[60:63], v[152:155], v[194:197], v[60:63]
	v_mfma_f32_16x16x32_bf16 v[56:59], v[160:163], v[194:197], v[56:59]
	v_mfma_f32_16x16x32_bf16 v[52:55], v[152:155], v[202:205], v[52:55]
	v_mfma_f32_16x16x32_bf16 v[48:51], v[160:163], v[202:205], v[48:51]
	v_mfma_f32_16x16x32_bf16 v[36:39], v[152:155], v[224:227], v[36:39]
	v_mfma_f32_16x16x32_bf16 v[32:35], v[160:163], v[224:227], v[32:35]
	v_mfma_f32_16x16x32_bf16 v[20:23], v[152:155], v[232:235], v[20:23]
	v_mfma_f32_16x16x32_bf16 v[16:19], v[160:163], v[232:235], v[16:19]
	s_setprio 0
	s_setprio 1
	v_mfma_f32_16x16x32_bf16 v[44:47], v[164:167], v[190:193], v[44:47]
	v_mfma_f32_16x16x32_bf16 v[40:43], v[172:175], v[190:193], v[40:43]
	v_mfma_f32_16x16x32_bf16 v[28:31], v[164:167], v[198:201], v[28:31]
	v_mfma_f32_16x16x32_bf16 v[24:27], v[172:175], v[198:201], v[24:27]
	v_mfma_f32_16x16x32_bf16 v[12:15], v[164:167], v[220:223], v[12:15]
	v_mfma_f32_16x16x32_bf16 v[8:11], v[172:175], v[220:223], v[8:11]
	v_mfma_f32_16x16x32_bf16 v[4:7], v[164:167], v[228:231], v[4:7]
	v_mfma_f32_16x16x32_bf16 v[0:3], v[172:175], v[228:231], v[0:3]
	v_mfma_f32_16x16x32_bf16 v[44:47], v[168:171], v[194:197], v[44:47]
	v_mfma_f32_16x16x32_bf16 v[40:43], v[186:189], v[194:197], v[40:43]
	v_mfma_f32_16x16x32_bf16 v[28:31], v[168:171], v[202:205], v[28:31]
	v_mfma_f32_16x16x32_bf16 v[24:27], v[186:189], v[202:205], v[24:27]
	v_mfma_f32_16x16x32_bf16 v[12:15], v[168:171], v[224:227], v[12:15]
	v_mfma_f32_16x16x32_bf16 v[8:11], v[186:189], v[224:227], v[8:11]
	v_mfma_f32_16x16x32_bf16 v[4:7], v[168:171], v[232:235], v[4:7]
	v_mfma_f32_16x16x32_bf16 v[0:3], v[186:189], v[232:235], v[0:3]
	s_setprio 0
	s_barrier
	v_or_b32_e32 v147, 0x18000, v145
	v_add_u32_e32 v152, 0x18400, v145
	ds_read_b128 v[148:151], v147
	ds_read_b128 v[152:155], v152
	v_add_u32_e32 v147, 0x18800, v145
	v_add_u32_e32 v160, 0x18c00, v145
	ds_read_b128 v[156:159], v147
	ds_read_b128 v[160:163], v160
	v_or_b32_e32 v147, 0x1c000, v145
	v_add_u32_e32 v168, 0x1c400, v145
	ds_read_b128 v[164:167], v147
	ds_read_b128 v[168:171], v168
	v_add_u32_e32 v147, 0x1c800, v145
	v_add_u32_e32 v186, 0x1cc00, v145
	ds_read_b128 v[172:175], v147
	ds_read_b128 v[186:189], v186
	s_add_u32 s6, s6, 0x40000
	s_addc_u32 s7, s7, 0
	s_mov_b32 m0, s25
	v_lshl_add_u64 v[244:245], s[6:7], 0, v[128:129]
	ds_read_b128 v[190:193], v144 offset:32768
	ds_read_b128 v[194:197], v144 offset:33792
	ds_read_b128 v[198:201], v144 offset:34816
	ds_read_b128 v[202:205], v144 offset:35840
	ds_read_b128 v[220:223], v144 offset:36864
	ds_read_b128 v[224:227], v144 offset:37888
	ds_read_b128 v[228:231], v144 offset:38912
	ds_read_b128 v[232:235], v144 offset:39936
	global_load_lds_dwordx4 v[244:245], off
	v_lshl_add_u64 v[244:245], s[6:7], 0, v[132:133]
	s_mov_b32 m0, s26
	s_nop 0
	global_load_lds_dwordx4 v[244:245], off
	s_waitcnt vmcnt(8)
	s_waitcnt lgkmcnt(0)
	s_barrier
	s_setprio 1
	s_waitcnt lgkmcnt(0)
	v_mfma_f32_16x16x32_bf16 v[124:127], v[148:151], v[190:193], v[124:127]
	v_mfma_f32_16x16x32_bf16 v[120:123], v[156:159], v[190:193], v[120:123]
	v_mfma_f32_16x16x32_bf16 v[116:119], v[148:151], v[198:201], v[116:119]
	v_mfma_f32_16x16x32_bf16 v[112:115], v[156:159], v[198:201], v[112:115]
	v_mfma_f32_16x16x32_bf16 v[100:103], v[148:151], v[220:223], v[100:103]
	v_mfma_f32_16x16x32_bf16 v[96:99], v[156:159], v[220:223], v[96:99]
	v_mfma_f32_16x16x32_bf16 v[84:87], v[148:151], v[228:231], v[84:87]
	v_mfma_f32_16x16x32_bf16 v[80:83], v[156:159], v[228:231], v[80:83]
	v_mfma_f32_16x16x32_bf16 v[124:127], v[152:155], v[194:197], v[124:127]
	v_mfma_f32_16x16x32_bf16 v[120:123], v[160:163], v[194:197], v[120:123]
	v_mfma_f32_16x16x32_bf16 v[116:119], v[152:155], v[202:205], v[116:119]
	v_mfma_f32_16x16x32_bf16 v[112:115], v[160:163], v[202:205], v[112:115]
	v_mfma_f32_16x16x32_bf16 v[100:103], v[152:155], v[224:227], v[100:103]
	v_mfma_f32_16x16x32_bf16 v[96:99], v[160:163], v[224:227], v[96:99]
	v_mfma_f32_16x16x32_bf16 v[84:87], v[152:155], v[232:235], v[84:87]
	v_mfma_f32_16x16x32_bf16 v[80:83], v[160:163], v[232:235], v[80:83]
	s_setprio 0
	s_setprio 1
	v_mfma_f32_16x16x32_bf16 v[108:111], v[164:167], v[190:193], v[108:111]
	v_mfma_f32_16x16x32_bf16 v[104:107], v[172:175], v[190:193], v[104:107]
	v_mfma_f32_16x16x32_bf16 v[92:95], v[164:167], v[198:201], v[92:95]
	v_mfma_f32_16x16x32_bf16 v[88:91], v[172:175], v[198:201], v[88:91]
	v_mfma_f32_16x16x32_bf16 v[76:79], v[164:167], v[220:223], v[76:79]
	v_mfma_f32_16x16x32_bf16 v[72:75], v[172:175], v[220:223], v[72:75]
	v_mfma_f32_16x16x32_bf16 v[68:71], v[164:167], v[228:231], v[68:71]
	v_mfma_f32_16x16x32_bf16 v[64:67], v[172:175], v[228:231], v[64:67]
	v_mfma_f32_16x16x32_bf16 v[108:111], v[168:171], v[194:197], v[108:111]
	v_mfma_f32_16x16x32_bf16 v[104:107], v[186:189], v[194:197], v[104:107]
	v_mfma_f32_16x16x32_bf16 v[92:95], v[168:171], v[202:205], v[92:95]
	v_mfma_f32_16x16x32_bf16 v[88:91], v[186:189], v[202:205], v[88:91]
	v_mfma_f32_16x16x32_bf16 v[76:79], v[168:171], v[224:227], v[76:79]
	v_mfma_f32_16x16x32_bf16 v[72:75], v[186:189], v[224:227], v[72:75]
	v_mfma_f32_16x16x32_bf16 v[68:71], v[168:171], v[232:235], v[68:71]
	v_mfma_f32_16x16x32_bf16 v[64:67], v[186:189], v[232:235], v[64:67]
	s_setprio 0
	s_barrier
	s_mov_b32 m0, s27
	v_lshl_add_u64 v[236:237], v[236:237], 0, s[0:1]
	s_add_u32 s2, s2, 0x40080
	ds_read_b128 v[190:193], v144 offset:49152
	ds_read_b128 v[194:197], v144 offset:50176
	ds_read_b128 v[198:201], v144 offset:51200
	ds_read_b128 v[202:205], v144 offset:52224
	ds_read_b128 v[220:223], v144 offset:53248
	ds_read_b128 v[224:227], v144 offset:54272
	ds_read_b128 v[228:231], v144 offset:55296
	ds_read_b128 v[232:235], v144 offset:56320
	global_load_lds_dwordx4 v[236:237], off
	v_lshl_add_u64 v[236:237], v[238:239], 0, s[0:1]
	s_mov_b32 m0, s28
	s_addc_u32 s3, s3, 0
	global_load_lds_dwordx4 v[236:237], off
	v_lshl_add_u64 v[236:237], s[2:3], 0, v[130:131]
	s_mov_b32 m0, s31
	s_nop 0
	global_load_lds_dwordx4 v[236:237], off
	v_lshl_add_u64 v[236:237], s[2:3], 0, v[134:135]
	s_mov_b32 m0, s34
	s_nop 0
	global_load_lds_dwordx4 v[236:237], off
	v_lshl_add_u64 v[236:237], v[240:241], 0, s[0:1]
	s_mov_b32 m0, s29
	s_nop 0
	global_load_lds_dwordx4 v[236:237], off
	v_lshl_add_u64 v[236:237], v[242:243], 0, s[0:1]
	s_mov_b32 m0, s30
	s_nop 0
	global_load_lds_dwordx4 v[236:237], off
	s_waitcnt vmcnt(8)
	s_waitcnt lgkmcnt(0)
	s_barrier
	s_setprio 1
	s_waitcnt lgkmcnt(0)
	v_mfma_f32_16x16x32_bf16 v[60:63], v[148:151], v[190:193], v[60:63]
	v_mfma_f32_16x16x32_bf16 v[56:59], v[156:159], v[190:193], v[56:59]
	v_mfma_f32_16x16x32_bf16 v[52:55], v[148:151], v[198:201], v[52:55]
	v_mfma_f32_16x16x32_bf16 v[48:51], v[156:159], v[198:201], v[48:51]
	v_mfma_f32_16x16x32_bf16 v[36:39], v[148:151], v[220:223], v[36:39]
	v_mfma_f32_16x16x32_bf16 v[32:35], v[156:159], v[220:223], v[32:35]
	v_mfma_f32_16x16x32_bf16 v[20:23], v[148:151], v[228:231], v[20:23]
	v_mfma_f32_16x16x32_bf16 v[16:19], v[156:159], v[228:231], v[16:19]
	v_mfma_f32_16x16x32_bf16 v[60:63], v[152:155], v[194:197], v[60:63]
	v_mfma_f32_16x16x32_bf16 v[56:59], v[160:163], v[194:197], v[56:59]
	v_mfma_f32_16x16x32_bf16 v[52:55], v[152:155], v[202:205], v[52:55]
	v_mfma_f32_16x16x32_bf16 v[48:51], v[160:163], v[202:205], v[48:51]
	v_mfma_f32_16x16x32_bf16 v[36:39], v[152:155], v[224:227], v[36:39]
	v_mfma_f32_16x16x32_bf16 v[32:35], v[160:163], v[224:227], v[32:35]
	v_mfma_f32_16x16x32_bf16 v[20:23], v[152:155], v[232:235], v[20:23]
	v_mfma_f32_16x16x32_bf16 v[16:19], v[160:163], v[232:235], v[16:19]
	s_setprio 0
	s_setprio 1
	v_mfma_f32_16x16x32_bf16 v[44:47], v[164:167], v[190:193], v[44:47]
	v_mfma_f32_16x16x32_bf16 v[40:43], v[172:175], v[190:193], v[40:43]
	v_mfma_f32_16x16x32_bf16 v[28:31], v[164:167], v[198:201], v[28:31]
	v_mfma_f32_16x16x32_bf16 v[24:27], v[172:175], v[198:201], v[24:27]
	v_mfma_f32_16x16x32_bf16 v[12:15], v[164:167], v[220:223], v[12:15]
	v_mfma_f32_16x16x32_bf16 v[8:11], v[172:175], v[220:223], v[8:11]
	v_mfma_f32_16x16x32_bf16 v[4:7], v[164:167], v[228:231], v[4:7]
	v_mfma_f32_16x16x32_bf16 v[0:3], v[172:175], v[228:231], v[0:3]
	v_mfma_f32_16x16x32_bf16 v[44:47], v[168:171], v[194:197], v[44:47]
	v_mfma_f32_16x16x32_bf16 v[40:43], v[186:189], v[194:197], v[40:43]
	v_mfma_f32_16x16x32_bf16 v[28:31], v[168:171], v[202:205], v[28:31]
	v_mfma_f32_16x16x32_bf16 v[24:27], v[186:189], v[202:205], v[24:27]
	v_mfma_f32_16x16x32_bf16 v[12:15], v[168:171], v[224:227], v[12:15]
	v_mfma_f32_16x16x32_bf16 v[8:11], v[186:189], v[224:227], v[8:11]
	v_mfma_f32_16x16x32_bf16 v[4:7], v[168:171], v[232:235], v[4:7]
	v_mfma_f32_16x16x32_bf16 v[0:3], v[186:189], v[232:235], v[0:3]
	s_setprio 0
	s_barrier
	s_add_i32 s95, s95, 2
	s_add_u32 s90, s90, 0x100
	s_addc_u32 s91, s91, 0
	s_add_u32 s92, s92, 0x100
	s_addc_u32 s94, s94, 0
	s_cmp_gt_u32 s95, 13
	s_cbranch_scc0 .LBB0_462
	s_and_b64 vcc, exec, s[40:41]
	s_cbranch_vccz .LBB0_465
	s_barrier
